# fused norm epilogues: f32 residual stores issued after the row-sum exchange instead of before it
# baseline (speedup 1.0000x reference)
.LBB0_361:
	s_mov_b32 s36, s69
	s_mov_b32 s37, s70
	v_lshl_add_u32 v128, s69, 8, v221
	v_lshl_or_b32 v136, s70, 8, v223
	s_load_dwordx2 s[22:23], s[92:93], 0x48
	s_load_dwordx2 s[24:25], s[92:93], 0xd8
	s_ashr_i32 s2, s69, 4
	v_lshlrev_b32_e32 v136, 2, v136
	s_mul_hi_i32 s32, s2, 0x9000
	s_mul_i32 s2, s2, 0x9000
	v_lshl_add_u32 v128, v128, 12, v136
	s_add_u32 s34, s52, s2
	s_addc_u32 s35, s53, s32
	v_add_u32_e32 v129, 0x10000, v128
	v_add_u32_e32 v130, 0x20000, v128
	v_add_u32_e32 v131, 0x30000, v128
	v_add_u32_e32 v132, 0x80000, v128
	v_add_u32_e32 v133, 0x90000, v128
	v_add_u32_e32 v134, 0xa0000, v128
	v_add_u32_e32 v135, 0xb0000, v128
	v_and_b32_e32 v137, 63, v230
	v_xor_b32_e32 v138, 32, v137
	v_xor_b32_e32 v137, 16, v137
	v_lshlrev_b32_e32 v138, 2, v138
	v_lshlrev_b32_e32 v137, 2, v137
	global_load_dwordx4 v[140:143], v136, s[34:35]
	global_load_dwordx4 v[144:147], v136, s[34:35] offset:64
	global_load_dwordx4 v[148:151], v136, s[34:35] offset:512
	global_load_dwordx4 v[152:155], v136, s[34:35] offset:576
	global_load_dwordx4 v[188:191], v128, s[0:1]
	global_load_dwordx4 v[192:195], v128, s[0:1] offset:64
	global_load_dwordx4 v[196:199], v128, s[0:1] offset:512
	global_load_dwordx4 v[200:203], v128, s[0:1] offset:576
	global_load_dwordx4 v[204:207], v129, s[0:1]
	global_load_dwordx4 v[208:211], v129, s[0:1] offset:64
	global_load_dwordx4 v[212:215], v129, s[0:1] offset:512
	global_load_dwordx4 v[216:219], v129, s[0:1] offset:576
	global_load_dwordx4 v[156:159], v130, s[0:1]
	global_load_dwordx4 v[160:163], v130, s[0:1] offset:64
	global_load_dwordx4 v[164:167], v130, s[0:1] offset:512
	global_load_dwordx4 v[168:171], v130, s[0:1] offset:576
	global_load_dwordx4 v[232:235], v131, s[0:1]
	global_load_dwordx4 v[236:239], v131, s[0:1] offset:64
	global_load_dwordx4 v[240:243], v131, s[0:1] offset:512
	global_load_dwordx4 v[244:247], v131, s[0:1] offset:576
	s_waitcnt lgkmcnt(0)
	s_add_u32 s72, s24, 0x3010000
	s_addc_u32 s73, s25, 0
	s_add_u32 s72, s72, s2
	s_addc_u32 s73, s73, s32
	s_add_u32 s76, s72, 0x4000
	s_addc_u32 s77, s73, 0
	s_add_u32 s78, s72, 0x3000
	s_addc_u32 s79, s73, 0
	s_add_u32 s74, s24, 0x86a0000
	s_addc_u32 s75, s25, 0
	s_add_u32 s24, s24, 0x32a0000
	s_addc_u32 s25, s25, 0
	s_add_u32 s26, s24, 0x100800
	s_addc_u32 s27, s25, 0
	s_waitcnt vmcnt(8)
	v_pk_mul_f32 v[140:141], v[140:141], 0.5 op_sel_hi:[1,0]
	v_pk_mul_f32 v[142:143], v[142:143], 0.5 op_sel_hi:[1,0]
	v_pk_mul_f32 v[144:145], v[144:145], 0.5 op_sel_hi:[1,0]
	v_pk_mul_f32 v[146:147], v[146:147], 0.5 op_sel_hi:[1,0]
	v_pk_mul_f32 v[148:149], v[148:149], 0.5 op_sel_hi:[1,0]
	v_pk_mul_f32 v[150:151], v[150:151], 0.5 op_sel_hi:[1,0]
	v_pk_mul_f32 v[152:153], v[152:153], 0.5 op_sel_hi:[1,0]
	v_pk_mul_f32 v[154:155], v[154:155], 0.5 op_sel_hi:[1,0]
	v_pk_fma_f32 v[124:125], v[124:125], v[140:141], v[188:189]
	v_pk_fma_f32 v[126:127], v[126:127], v[142:143], v[190:191]
	v_pk_mul_f32 v[248:249], v[124:125], v[124:125]
	v_pk_fma_f32 v[248:249], v[126:127], v[126:127], v[248:249]
	v_pk_fma_f32 v[104:105], v[104:105], v[144:145], v[192:193]
	v_pk_fma_f32 v[106:107], v[106:107], v[146:147], v[194:195]
	v_pk_fma_f32 v[248:249], v[104:105], v[104:105], v[248:249]
	v_pk_fma_f32 v[248:249], v[106:107], v[106:107], v[248:249]
	v_pk_fma_f32 v[68:69], v[68:69], v[148:149], v[196:197]
	v_pk_fma_f32 v[70:71], v[70:71], v[150:151], v[198:199]
	v_pk_fma_f32 v[248:249], v[68:69], v[68:69], v[248:249]
	v_pk_fma_f32 v[248:249], v[70:71], v[70:71], v[248:249]
	v_pk_fma_f32 v[44:45], v[44:45], v[152:153], v[200:201]
	v_pk_fma_f32 v[46:47], v[46:47], v[154:155], v[202:203]
	v_pk_fma_f32 v[248:249], v[44:45], v[44:45], v[248:249]
	v_pk_fma_f32 v[248:249], v[46:47], v[46:47], v[248:249]
	s_nop 0
	v_add_f32_e32 v172, v248, v249
	v_pk_fma_f32 v[120:121], v[120:121], v[140:141], v[204:205]
	v_pk_fma_f32 v[122:123], v[122:123], v[142:143], v[206:207]
	v_pk_mul_f32 v[248:249], v[120:121], v[120:121]
	v_pk_fma_f32 v[248:249], v[122:123], v[122:123], v[248:249]
	v_pk_fma_f32 v[96:97], v[96:97], v[144:145], v[208:209]
	v_pk_fma_f32 v[98:99], v[98:99], v[146:147], v[210:211]
	v_pk_fma_f32 v[248:249], v[96:97], v[96:97], v[248:249]
	v_pk_fma_f32 v[248:249], v[98:99], v[98:99], v[248:249]
	v_pk_fma_f32 v[64:65], v[64:65], v[148:149], v[212:213]
	v_pk_fma_f32 v[66:67], v[66:67], v[150:151], v[214:215]
	v_pk_fma_f32 v[248:249], v[64:65], v[64:65], v[248:249]
	v_pk_fma_f32 v[248:249], v[66:67], v[66:67], v[248:249]
	v_pk_fma_f32 v[36:37], v[36:37], v[152:153], v[216:217]
	v_pk_fma_f32 v[38:39], v[38:39], v[154:155], v[218:219]
	v_pk_fma_f32 v[248:249], v[36:37], v[36:37], v[248:249]
	v_pk_fma_f32 v[248:249], v[38:39], v[38:39], v[248:249]
	s_nop 0
	v_add_f32_e32 v173, v248, v249
	s_nop 1
	global_load_dwordx4 v[188:191], v132, s[0:1]
	global_load_dwordx4 v[192:195], v132, s[0:1] offset:64
	global_load_dwordx4 v[196:199], v132, s[0:1] offset:512
	global_load_dwordx4 v[200:203], v132, s[0:1] offset:576
	global_load_dwordx4 v[204:207], v133, s[0:1]
	global_load_dwordx4 v[208:211], v133, s[0:1] offset:64
	global_load_dwordx4 v[212:215], v133, s[0:1] offset:512
	global_load_dwordx4 v[216:219], v133, s[0:1] offset:576
	s_waitcnt vmcnt(8)
	v_pk_fma_f32 v[116:117], v[116:117], v[140:141], v[156:157]
	v_pk_fma_f32 v[118:119], v[118:119], v[142:143], v[158:159]
	v_pk_mul_f32 v[248:249], v[116:117], v[116:117]
	v_pk_fma_f32 v[248:249], v[118:119], v[118:119], v[248:249]
	v_pk_fma_f32 v[88:89], v[88:89], v[144:145], v[160:161]
	v_pk_fma_f32 v[90:91], v[90:91], v[146:147], v[162:163]
	v_pk_fma_f32 v[248:249], v[88:89], v[88:89], v[248:249]
	v_pk_fma_f32 v[248:249], v[90:91], v[90:91], v[248:249]
	v_pk_fma_f32 v[52:53], v[52:53], v[148:149], v[164:165]
	v_pk_fma_f32 v[54:55], v[54:55], v[150:151], v[166:167]
	v_pk_fma_f32 v[248:249], v[52:53], v[52:53], v[248:249]
	v_pk_fma_f32 v[248:249], v[54:55], v[54:55], v[248:249]
	v_pk_fma_f32 v[28:29], v[28:29], v[152:153], v[168:169]
	v_pk_fma_f32 v[30:31], v[30:31], v[154:155], v[170:171]
	v_pk_fma_f32 v[248:249], v[28:29], v[28:29], v[248:249]
	v_pk_fma_f32 v[248:249], v[30:31], v[30:31], v[248:249]
	s_nop 0
	v_add_f32_e32 v174, v248, v249
	v_pk_fma_f32 v[112:113], v[112:113], v[140:141], v[232:233]
	v_pk_fma_f32 v[114:115], v[114:115], v[142:143], v[234:235]
	v_pk_mul_f32 v[248:249], v[112:113], v[112:113]
	v_pk_fma_f32 v[248:249], v[114:115], v[114:115], v[248:249]
	v_pk_fma_f32 v[80:81], v[80:81], v[144:145], v[236:237]
	v_pk_fma_f32 v[82:83], v[82:83], v[146:147], v[238:239]
	v_pk_fma_f32 v[248:249], v[80:81], v[80:81], v[248:249]
	v_pk_fma_f32 v[248:249], v[82:83], v[82:83], v[248:249]
	v_pk_fma_f32 v[48:49], v[48:49], v[148:149], v[240:241]
	v_pk_fma_f32 v[50:51], v[50:51], v[150:151], v[242:243]
	v_pk_fma_f32 v[248:249], v[48:49], v[48:49], v[248:249]
	v_pk_fma_f32 v[248:249], v[50:51], v[50:51], v[248:249]
	v_pk_fma_f32 v[20:21], v[20:21], v[152:153], v[244:245]
	v_pk_fma_f32 v[22:23], v[22:23], v[154:155], v[246:247]
	v_pk_fma_f32 v[248:249], v[20:21], v[20:21], v[248:249]
	v_pk_fma_f32 v[248:249], v[22:23], v[22:23], v[248:249]
	s_nop 0
	v_add_f32_e32 v175, v248, v249
	s_nop 1
	global_load_dwordx4 v[156:159], v134, s[0:1]
	global_load_dwordx4 v[160:163], v134, s[0:1] offset:64
	global_load_dwordx4 v[164:167], v134, s[0:1] offset:512
	global_load_dwordx4 v[168:171], v134, s[0:1] offset:576
	global_load_dwordx4 v[232:235], v135, s[0:1]
	global_load_dwordx4 v[236:239], v135, s[0:1] offset:64
	global_load_dwordx4 v[240:243], v135, s[0:1] offset:512
	global_load_dwordx4 v[244:247], v135, s[0:1] offset:576
	s_waitcnt vmcnt(8)
	v_pk_fma_f32 v[108:109], v[108:109], v[140:141], v[188:189]
	v_pk_fma_f32 v[110:111], v[110:111], v[142:143], v[190:191]
	v_pk_mul_f32 v[248:249], v[108:109], v[108:109]
	v_pk_fma_f32 v[248:249], v[110:111], v[110:111], v[248:249]
	v_pk_fma_f32 v[76:77], v[76:77], v[144:145], v[192:193]
	v_pk_fma_f32 v[78:79], v[78:79], v[146:147], v[194:195]
	v_pk_fma_f32 v[248:249], v[76:77], v[76:77], v[248:249]
	v_pk_fma_f32 v[248:249], v[78:79], v[78:79], v[248:249]
	v_pk_fma_f32 v[40:41], v[40:41], v[148:149], v[196:197]
	v_pk_fma_f32 v[42:43], v[42:43], v[150:151], v[198:199]
	v_pk_fma_f32 v[248:249], v[40:41], v[40:41], v[248:249]
	v_pk_fma_f32 v[248:249], v[42:43], v[42:43], v[248:249]
	v_pk_fma_f32 v[12:13], v[12:13], v[152:153], v[200:201]
	v_pk_fma_f32 v[14:15], v[14:15], v[154:155], v[202:203]
	v_pk_fma_f32 v[248:249], v[12:13], v[12:13], v[248:249]
	v_pk_fma_f32 v[248:249], v[14:15], v[14:15], v[248:249]
	s_nop 0
	v_add_f32_e32 v227, v248, v249
	v_pk_fma_f32 v[100:101], v[100:101], v[140:141], v[204:205]
	v_pk_fma_f32 v[102:103], v[102:103], v[142:143], v[206:207]
	v_pk_mul_f32 v[248:249], v[100:101], v[100:101]
	v_pk_fma_f32 v[248:249], v[102:103], v[102:103], v[248:249]
	v_pk_fma_f32 v[72:73], v[72:73], v[144:145], v[208:209]
	v_pk_fma_f32 v[74:75], v[74:75], v[146:147], v[210:211]
	v_pk_fma_f32 v[248:249], v[72:73], v[72:73], v[248:249]
	v_pk_fma_f32 v[248:249], v[74:75], v[74:75], v[248:249]
	v_pk_fma_f32 v[32:33], v[32:33], v[148:149], v[212:213]
	v_pk_fma_f32 v[34:35], v[34:35], v[150:151], v[214:215]
	v_pk_fma_f32 v[248:249], v[32:33], v[32:33], v[248:249]
	v_pk_fma_f32 v[248:249], v[34:35], v[34:35], v[248:249]
	v_pk_fma_f32 v[8:9], v[8:9], v[152:153], v[216:217]
	v_pk_fma_f32 v[10:11], v[10:11], v[154:155], v[218:219]
	v_pk_fma_f32 v[248:249], v[8:9], v[8:9], v[248:249]
	v_pk_fma_f32 v[248:249], v[10:11], v[10:11], v[248:249]
	s_nop 0
	v_add_f32_e32 v228, v248, v249
	s_waitcnt vmcnt(0)
	v_pk_fma_f32 v[92:93], v[92:93], v[140:141], v[156:157]
	v_pk_fma_f32 v[94:95], v[94:95], v[142:143], v[158:159]
	v_pk_mul_f32 v[248:249], v[92:93], v[92:93]
	v_pk_fma_f32 v[248:249], v[94:95], v[94:95], v[248:249]
	v_pk_fma_f32 v[60:61], v[60:61], v[144:145], v[160:161]
	v_pk_fma_f32 v[62:63], v[62:63], v[146:147], v[162:163]
	v_pk_fma_f32 v[248:249], v[60:61], v[60:61], v[248:249]
	v_pk_fma_f32 v[248:249], v[62:63], v[62:63], v[248:249]
	v_pk_fma_f32 v[24:25], v[24:25], v[148:149], v[164:165]
	v_pk_fma_f32 v[26:27], v[26:27], v[150:151], v[166:167]
	v_pk_fma_f32 v[248:249], v[24:25], v[24:25], v[248:249]
	v_pk_fma_f32 v[248:249], v[26:27], v[26:27], v[248:249]
	v_pk_fma_f32 v[4:5], v[4:5], v[152:153], v[168:169]
	v_pk_fma_f32 v[6:7], v[6:7], v[154:155], v[170:171]
	v_pk_fma_f32 v[248:249], v[4:5], v[4:5], v[248:249]
	v_pk_fma_f32 v[248:249], v[6:7], v[6:7], v[248:249]
	s_nop 0
	v_add_f32_e32 v229, v248, v249
	v_pk_fma_f32 v[84:85], v[84:85], v[140:141], v[232:233]
	v_pk_fma_f32 v[86:87], v[86:87], v[142:143], v[234:235]
	v_pk_mul_f32 v[248:249], v[84:85], v[84:85]
	v_pk_fma_f32 v[248:249], v[86:87], v[86:87], v[248:249]
	v_pk_fma_f32 v[56:57], v[56:57], v[144:145], v[236:237]
	v_pk_fma_f32 v[58:59], v[58:59], v[146:147], v[238:239]
	v_pk_fma_f32 v[248:249], v[56:57], v[56:57], v[248:249]
	v_pk_fma_f32 v[248:249], v[58:59], v[58:59], v[248:249]
	v_pk_fma_f32 v[16:17], v[16:17], v[148:149], v[240:241]
	v_pk_fma_f32 v[18:19], v[18:19], v[150:151], v[242:243]
	v_pk_fma_f32 v[248:249], v[16:17], v[16:17], v[248:249]
	v_pk_fma_f32 v[248:249], v[18:19], v[18:19], v[248:249]
	v_pk_fma_f32 v[0:1], v[0:1], v[152:153], v[244:245]
	v_pk_fma_f32 v[2:3], v[2:3], v[154:155], v[246:247]
	v_pk_fma_f32 v[248:249], v[0:1], v[0:1], v[248:249]
	v_pk_fma_f32 v[248:249], v[2:3], v[2:3], v[248:249]
	s_nop 0
	v_add_f32_e32 v231, v248, v249
	ds_bpermute_b32 v188, v137, v172
	ds_bpermute_b32 v189, v137, v173
	ds_bpermute_b32 v190, v137, v174
	ds_bpermute_b32 v191, v137, v175
	ds_bpermute_b32 v192, v137, v227
	ds_bpermute_b32 v193, v137, v228
	ds_bpermute_b32 v194, v137, v229
	ds_bpermute_b32 v195, v137, v231
	s_waitcnt lgkmcnt(0)
	v_add_f32_e32 v172, v172, v188
	v_add_f32_e32 v173, v173, v189
	v_add_f32_e32 v174, v174, v190
	v_add_f32_e32 v175, v175, v191
	v_add_f32_e32 v227, v227, v192
	v_add_f32_e32 v228, v228, v193
	v_add_f32_e32 v229, v229, v194
	v_add_f32_e32 v231, v231, v195
	ds_bpermute_b32 v188, v138, v172
	ds_bpermute_b32 v189, v138, v173
	ds_bpermute_b32 v190, v138, v174
	ds_bpermute_b32 v191, v138, v175
	ds_bpermute_b32 v192, v138, v227
	ds_bpermute_b32 v193, v138, v228
	ds_bpermute_b32 v194, v138, v229
	ds_bpermute_b32 v195, v138, v231
	s_waitcnt lgkmcnt(0)
	v_add_f32_e32 v172, v172, v188
	v_add_f32_e32 v173, v173, v189
	v_add_f32_e32 v174, v174, v190
	v_add_f32_e32 v175, v175, v191
	v_add_f32_e32 v227, v227, v192
	v_add_f32_e32 v228, v228, v193
	v_add_f32_e32 v229, v229, v194
	v_add_f32_e32 v231, v231, v195
	v_lshrrev_b32_e32 v140, 5, v223
	v_and_b32_e32 v140, 3, v140
	v_lshlrev_b32_e32 v142, 4, v221
	v_add_u32_e32 v142, 0x20400, v142
	v_lshl_add_u32 v141, v140, 2, v142
	v_lshl_add_u32 v144, s36, 8, v221
	v_lshlrev_b32_e32 v144, 4, v144
	v_mov_b32_e32 v143, s37
	v_lshl_add_u32 v143, v143, 2, v144
	s_mov_b64 exec, 0xffff
	ds_write_b32 v141, v172
	ds_write_b32 v141, v173 offset:256
	ds_write_b32 v141, v174 offset:512
	ds_write_b32 v141, v175 offset:768
	ds_write_b32 v141, v227 offset:2048
	ds_write_b32 v141, v228 offset:2304
	ds_write_b32 v141, v229 offset:2560
	ds_write_b32 v141, v231 offset:2816
	s_mov_b64 exec, -1
	s_waitcnt lgkmcnt(0)
	s_barrier
	ds_read_b128 v[156:159], v142
	ds_read_b128 v[160:163], v142 offset:256
	ds_read_b128 v[164:167], v142 offset:512
	ds_read_b128 v[168:171], v142 offset:768
	ds_read_b128 v[232:235], v142 offset:2048
	ds_read_b128 v[236:239], v142 offset:2304
	ds_read_b128 v[240:243], v142 offset:2560
	ds_read_b128 v[244:247], v142 offset:2816
	s_waitcnt lgkmcnt(0)
	v_add_f32_e32 v248, v156, v157
	v_add_f32_e32 v249, v158, v159
	v_add_f32_e32 v172, v248, v249
	v_add_f32_e32 v248, v160, v161
	v_add_f32_e32 v249, v162, v163
	v_add_f32_e32 v173, v248, v249
	v_add_f32_e32 v248, v164, v165
	v_add_f32_e32 v249, v166, v167
	v_add_f32_e32 v174, v248, v249
	v_add_f32_e32 v248, v168, v169
	v_add_f32_e32 v249, v170, v171
	v_add_f32_e32 v175, v248, v249
	v_add_f32_e32 v248, v232, v233
	v_add_f32_e32 v249, v234, v235
	v_add_f32_e32 v227, v248, v249
	v_add_f32_e32 v248, v236, v237
	v_add_f32_e32 v249, v238, v239
	v_add_f32_e32 v228, v248, v249
	v_add_f32_e32 v248, v240, v241
	v_add_f32_e32 v249, v242, v243
	v_add_f32_e32 v229, v248, v249
	v_add_f32_e32 v248, v244, v245
	v_add_f32_e32 v249, v246, v247
	v_add_f32_e32 v231, v248, v249
	v_readfirstlane_b32 s84, v140
	s_nop 0
	s_cmp_lg_u32 s84, 0
	s_cbranch_scc1 .Lfn_nosw_p2
	s_mov_b64 exec, 0xffff
	global_atomic_swap v143, v172, s[24:25]
	global_atomic_swap v143, v173, s[24:25] offset:256
	global_atomic_swap v143, v174, s[24:25] offset:512
	global_atomic_swap v143, v175, s[24:25] offset:768
	global_atomic_swap v143, v227, s[24:25] offset:2048
	global_atomic_swap v143, v228, s[24:25] offset:2304
	global_atomic_swap v143, v229, s[24:25] offset:2560
	global_atomic_swap v143, v231, s[24:25] offset:2816
	s_mov_b64 exec, -1

.Lfn_meet_p2:
	s_or_b64 exec, exec, s[82:83]
	s_barrier
	global_load_dwordx4 v[156:159], v144, s[24:25] sc1
	global_load_dwordx4 v[160:163], v144, s[24:25] offset:256 sc1
	global_load_dwordx4 v[164:167], v144, s[24:25] offset:512 sc1
	global_load_dwordx4 v[168:171], v144, s[24:25] offset:768 sc1
	global_load_dwordx4 v[232:235], v144, s[24:25] offset:2048 sc1
	global_load_dwordx4 v[236:239], v144, s[24:25] offset:2304 sc1
	global_load_dwordx4 v[240:243], v144, s[24:25] offset:2560 sc1
	global_load_dwordx4 v[244:247], v144, s[24:25] offset:2816 sc1
	s_waitcnt vmcnt(0)
	v_add_f32_e32 v248, v156, v157
	v_add_f32_e32 v249, v158, v159
	v_add_f32_e32 v146, v248, v249
	v_add_f32_e32 v248, v160, v161
	v_add_f32_e32 v249, v162, v163
	v_add_f32_e32 v147, v248, v249
	v_add_f32_e32 v248, v164, v165
	v_add_f32_e32 v249, v166, v167
	v_add_f32_e32 v148, v248, v249
	v_add_f32_e32 v248, v168, v169
	v_add_f32_e32 v249, v170, v171
	v_add_f32_e32 v149, v248, v249
	v_add_f32_e32 v248, v232, v233
	v_add_f32_e32 v249, v234, v235
	v_add_f32_e32 v150, v248, v249
	v_add_f32_e32 v248, v236, v237
	v_add_f32_e32 v249, v238, v239
	v_add_f32_e32 v151, v248, v249
	v_add_f32_e32 v248, v240, v241
	v_add_f32_e32 v249, v242, v243
	v_add_f32_e32 v152, v248, v249
	v_add_f32_e32 v248, v244, v245
	v_add_f32_e32 v249, v246, v247
	v_add_f32_e32 v153, v248, v249
	global_load_dwordx4 v[188:191], v136, s[22:23]
	global_load_dwordx4 v[192:195], v136, s[22:23] offset:64
	global_load_dwordx4 v[196:199], v136, s[22:23] offset:512
	global_load_dwordx4 v[200:203], v136, s[22:23] offset:576
	global_load_dwordx4 v[156:159], v136, s[76:77]
	global_load_dwordx4 v[160:163], v136, s[76:77] offset:64
	global_load_dwordx4 v[164:167], v136, s[76:77] offset:512
	global_load_dwordx4 v[168:171], v136, s[76:77] offset:576
	global_load_dwordx4 v[232:235], v136, s[78:79]
	global_load_dwordx4 v[236:239], v136, s[78:79] offset:64
	global_load_dwordx4 v[240:243], v136, s[78:79] offset:512
	global_load_dwordx4 v[244:247], v136, s[78:79] offset:576
	v_mov_b32_e32 v229, 0x358637bd
	v_mov_b32_e32 v231, 0x260
	s_mov_b32 s39, 0xf800000
	v_fmamk_f32 v146, v146, 0x3a800000, v229
	v_mul_f32_e32 v172, 0x4f800000, v146
	v_cmp_gt_f32_e32 vcc, s39, v146
	s_nop 1
	v_cndmask_b32_e32 v146, v146, v172, vcc
	v_sqrt_f32_e32 v173, v146
	s_nop 1
	v_add_u32_e32 v174, -1, v173
	v_add_u32_e32 v175, 1, v173
	v_fma_f32 v227, -v174, v173, v146
	v_fma_f32 v228, -v175, v173, v146
	v_cmp_ge_f32_e64 s[12:13], 0, v227
	s_nop 1
	v_cndmask_b32_e64 v173, v173, v174, s[12:13]
	v_cmp_lt_f32_e64 s[12:13], 0, v228
	s_nop 1
	v_cndmask_b32_e64 v173, v173, v175, s[12:13]
	v_mul_f32_e32 v174, 0x37800000, v173
	v_cndmask_b32_e32 v173, v173, v174, vcc
	v_cmp_class_f32_e32 vcc, v146, v231
	s_nop 1
	v_cndmask_b32_e32 v146, v173, v146, vcc
	v_div_scale_f32 v172, s[12:13], v146, v146, 1.0
	v_rcp_f32_e32 v173, v172
	v_div_scale_f32 v174, vcc, 1.0, v146, 1.0
	v_fma_f32 v175, -v172, v173, 1.0
	v_fmac_f32_e32 v173, v175, v173
	v_mul_f32_e32 v175, v174, v173
	v_fma_f32 v227, -v172, v175, v174
	v_fmac_f32_e32 v175, v227, v173
	v_fma_f32 v172, -v172, v175, v174
	v_div_fmas_f32 v175, v172, v173, v175
	v_div_fixup_f32 v204, v175, v146, 1.0
	v_fmamk_f32 v147, v147, 0x3a800000, v229
	v_mul_f32_e32 v172, 0x4f800000, v147
	v_cmp_gt_f32_e32 vcc, s39, v147
	s_nop 1
	v_cndmask_b32_e32 v147, v147, v172, vcc
	v_sqrt_f32_e32 v173, v147
	s_nop 1
	v_add_u32_e32 v174, -1, v173
	v_add_u32_e32 v175, 1, v173
	v_fma_f32 v227, -v174, v173, v147
	v_fma_f32 v228, -v175, v173, v147
	v_cmp_ge_f32_e64 s[12:13], 0, v227
	s_nop 1
	v_cndmask_b32_e64 v173, v173, v174, s[12:13]
	v_cmp_lt_f32_e64 s[12:13], 0, v228
	s_nop 1
	v_cndmask_b32_e64 v173, v173, v175, s[12:13]
	v_mul_f32_e32 v174, 0x37800000, v173
	v_cndmask_b32_e32 v173, v173, v174, vcc
	v_cmp_class_f32_e32 vcc, v147, v231
	s_nop 1
	v_cndmask_b32_e32 v147, v173, v147, vcc
	v_div_scale_f32 v172, s[12:13], v147, v147, 1.0
	v_rcp_f32_e32 v173, v172
	v_div_scale_f32 v174, vcc, 1.0, v147, 1.0
	v_fma_f32 v175, -v172, v173, 1.0
	v_fmac_f32_e32 v173, v175, v173
	v_mul_f32_e32 v175, v174, v173
	v_fma_f32 v227, -v172, v175, v174
	v_fmac_f32_e32 v175, v227, v173
	v_fma_f32 v172, -v172, v175, v174
	v_div_fmas_f32 v175, v172, v173, v175
	v_div_fixup_f32 v206, v175, v147, 1.0
	v_fmamk_f32 v148, v148, 0x3a800000, v229
	v_mul_f32_e32 v172, 0x4f800000, v148
	v_cmp_gt_f32_e32 vcc, s39, v148
	s_nop 1
	v_cndmask_b32_e32 v148, v148, v172, vcc
	v_sqrt_f32_e32 v173, v148
	s_nop 1
	v_add_u32_e32 v174, -1, v173
	v_add_u32_e32 v175, 1, v173
	v_fma_f32 v227, -v174, v173, v148
	v_fma_f32 v228, -v175, v173, v148
	v_cmp_ge_f32_e64 s[12:13], 0, v227
	s_nop 1
	v_cndmask_b32_e64 v173, v173, v174, s[12:13]
	v_cmp_lt_f32_e64 s[12:13], 0, v228
	s_nop 1
	v_cndmask_b32_e64 v173, v173, v175, s[12:13]
	v_mul_f32_e32 v174, 0x37800000, v173
	v_cndmask_b32_e32 v173, v173, v174, vcc
	v_cmp_class_f32_e32 vcc, v148, v231
	s_nop 1
	v_cndmask_b32_e32 v148, v173, v148, vcc
	v_div_scale_f32 v172, s[12:13], v148, v148, 1.0
	v_rcp_f32_e32 v173, v172
	v_div_scale_f32 v174, vcc, 1.0, v148, 1.0
	v_fma_f32 v175, -v172, v173, 1.0
	v_fmac_f32_e32 v173, v175, v173
	v_mul_f32_e32 v175, v174, v173
	v_fma_f32 v227, -v172, v175, v174
	v_fmac_f32_e32 v175, v227, v173
	v_fma_f32 v172, -v172, v175, v174
	v_div_fmas_f32 v175, v172, v173, v175
	v_div_fixup_f32 v208, v175, v148, 1.0
	v_fmamk_f32 v149, v149, 0x3a800000, v229
	v_mul_f32_e32 v172, 0x4f800000, v149
	v_cmp_gt_f32_e32 vcc, s39, v149
	s_nop 1
	v_cndmask_b32_e32 v149, v149, v172, vcc
	v_sqrt_f32_e32 v173, v149
	s_nop 1
	v_add_u32_e32 v174, -1, v173
	v_add_u32_e32 v175, 1, v173
	v_fma_f32 v227, -v174, v173, v149
	v_fma_f32 v228, -v175, v173, v149
	v_cmp_ge_f32_e64 s[12:13], 0, v227
	s_nop 1
	v_cndmask_b32_e64 v173, v173, v174, s[12:13]
	v_cmp_lt_f32_e64 s[12:13], 0, v228
	s_nop 1
	v_cndmask_b32_e64 v173, v173, v175, s[12:13]
	v_mul_f32_e32 v174, 0x37800000, v173
	v_cndmask_b32_e32 v173, v173, v174, vcc
	v_cmp_class_f32_e32 vcc, v149, v231
	s_nop 1
	v_cndmask_b32_e32 v149, v173, v149, vcc
	v_div_scale_f32 v172, s[12:13], v149, v149, 1.0
	v_rcp_f32_e32 v173, v172
	v_div_scale_f32 v174, vcc, 1.0, v149, 1.0
	v_fma_f32 v175, -v172, v173, 1.0
	v_fmac_f32_e32 v173, v175, v173
	v_mul_f32_e32 v175, v174, v173
	v_fma_f32 v227, -v172, v175, v174
	v_fmac_f32_e32 v175, v227, v173
	v_fma_f32 v172, -v172, v175, v174
	v_div_fmas_f32 v175, v172, v173, v175
	v_div_fixup_f32 v210, v175, v149, 1.0
	v_fmamk_f32 v150, v150, 0x3a800000, v229
	v_mul_f32_e32 v172, 0x4f800000, v150
	v_cmp_gt_f32_e32 vcc, s39, v150
	s_nop 1
	v_cndmask_b32_e32 v150, v150, v172, vcc
	v_sqrt_f32_e32 v173, v150
	s_nop 1
	v_add_u32_e32 v174, -1, v173
	v_add_u32_e32 v175, 1, v173
	v_fma_f32 v227, -v174, v173, v150
	v_fma_f32 v228, -v175, v173, v150
	v_cmp_ge_f32_e64 s[12:13], 0, v227
	s_nop 1
	v_cndmask_b32_e64 v173, v173, v174, s[12:13]
	v_cmp_lt_f32_e64 s[12:13], 0, v228
	s_nop 1
	v_cndmask_b32_e64 v173, v173, v175, s[12:13]
	v_mul_f32_e32 v174, 0x37800000, v173
	v_cndmask_b32_e32 v173, v173, v174, vcc
	v_cmp_class_f32_e32 vcc, v150, v231
	s_nop 1
	v_cndmask_b32_e32 v150, v173, v150, vcc
	v_div_scale_f32 v172, s[12:13], v150, v150, 1.0
	v_rcp_f32_e32 v173, v172
	v_div_scale_f32 v174, vcc, 1.0, v150, 1.0
	v_fma_f32 v175, -v172, v173, 1.0
	v_fmac_f32_e32 v173, v175, v173
	v_mul_f32_e32 v175, v174, v173
	v_fma_f32 v227, -v172, v175, v174
	v_fmac_f32_e32 v175, v227, v173
	v_fma_f32 v172, -v172, v175, v174
	v_div_fmas_f32 v175, v172, v173, v175
	v_div_fixup_f32 v212, v175, v150, 1.0
	v_fmamk_f32 v151, v151, 0x3a800000, v229
	v_mul_f32_e32 v172, 0x4f800000, v151
	v_cmp_gt_f32_e32 vcc, s39, v151
	s_nop 1
	v_cndmask_b32_e32 v151, v151, v172, vcc
	v_sqrt_f32_e32 v173, v151
	s_nop 1
	v_add_u32_e32 v174, -1, v173
	v_add_u32_e32 v175, 1, v173
	v_fma_f32 v227, -v174, v173, v151
	v_fma_f32 v228, -v175, v173, v151
	v_cmp_ge_f32_e64 s[12:13], 0, v227
	s_nop 1
	v_cndmask_b32_e64 v173, v173, v174, s[12:13]
	v_cmp_lt_f32_e64 s[12:13], 0, v228
	s_nop 1
	v_cndmask_b32_e64 v173, v173, v175, s[12:13]
	v_mul_f32_e32 v174, 0x37800000, v173
	v_cndmask_b32_e32 v173, v173, v174, vcc
	v_cmp_class_f32_e32 vcc, v151, v231
	s_nop 1
	v_cndmask_b32_e32 v151, v173, v151, vcc
	v_div_scale_f32 v172, s[12:13], v151, v151, 1.0
	v_rcp_f32_e32 v173, v172
	v_div_scale_f32 v174, vcc, 1.0, v151, 1.0
	v_fma_f32 v175, -v172, v173, 1.0
	v_fmac_f32_e32 v173, v175, v173
	v_mul_f32_e32 v175, v174, v173
	v_fma_f32 v227, -v172, v175, v174
	v_fmac_f32_e32 v175, v227, v173
	v_fma_f32 v172, -v172, v175, v174
	v_div_fmas_f32 v175, v172, v173, v175
	v_div_fixup_f32 v214, v175, v151, 1.0
	v_fmamk_f32 v152, v152, 0x3a800000, v229
	v_mul_f32_e32 v172, 0x4f800000, v152
	v_cmp_gt_f32_e32 vcc, s39, v152
	s_nop 1
	v_cndmask_b32_e32 v152, v152, v172, vcc
	v_sqrt_f32_e32 v173, v152
	s_nop 1
	v_add_u32_e32 v174, -1, v173
	v_add_u32_e32 v175, 1, v173
	v_fma_f32 v227, -v174, v173, v152
	v_fma_f32 v228, -v175, v173, v152
	v_cmp_ge_f32_e64 s[12:13], 0, v227
	s_nop 1
	v_cndmask_b32_e64 v173, v173, v174, s[12:13]
	v_cmp_lt_f32_e64 s[12:13], 0, v228
	s_nop 1
	v_cndmask_b32_e64 v173, v173, v175, s[12:13]
	v_mul_f32_e32 v174, 0x37800000, v173
	v_cndmask_b32_e32 v173, v173, v174, vcc
	v_cmp_class_f32_e32 vcc, v152, v231
	s_nop 1
	v_cndmask_b32_e32 v152, v173, v152, vcc
	v_div_scale_f32 v172, s[12:13], v152, v152, 1.0
	v_rcp_f32_e32 v173, v172
	v_div_scale_f32 v174, vcc, 1.0, v152, 1.0
	v_fma_f32 v175, -v172, v173, 1.0
	v_fmac_f32_e32 v173, v175, v173
	v_mul_f32_e32 v175, v174, v173
	v_fma_f32 v227, -v172, v175, v174
	v_fmac_f32_e32 v175, v227, v173
	v_fma_f32 v172, -v172, v175, v174
	v_div_fmas_f32 v175, v172, v173, v175
	v_div_fixup_f32 v216, v175, v152, 1.0
	v_fmamk_f32 v153, v153, 0x3a800000, v229
	v_mul_f32_e32 v172, 0x4f800000, v153
	v_cmp_gt_f32_e32 vcc, s39, v153
	s_nop 1
	v_cndmask_b32_e32 v153, v153, v172, vcc
	v_sqrt_f32_e32 v173, v153
	s_nop 1
	v_add_u32_e32 v174, -1, v173
	v_add_u32_e32 v175, 1, v173
	v_fma_f32 v227, -v174, v173, v153
	v_fma_f32 v228, -v175, v173, v153
	v_cmp_ge_f32_e64 s[12:13], 0, v227
	s_nop 1
	v_cndmask_b32_e64 v173, v173, v174, s[12:13]
	v_cmp_lt_f32_e64 s[12:13], 0, v228
	s_nop 1
	v_cndmask_b32_e64 v173, v173, v175, s[12:13]
	v_mul_f32_e32 v174, 0x37800000, v173
	v_cndmask_b32_e32 v173, v173, v174, vcc
	v_cmp_class_f32_e32 vcc, v153, v231
	s_nop 1
	v_cndmask_b32_e32 v153, v173, v153, vcc
	v_div_scale_f32 v172, s[12:13], v153, v153, 1.0
	v_rcp_f32_e32 v173, v172
	v_div_scale_f32 v174, vcc, 1.0, v153, 1.0
	v_fma_f32 v175, -v172, v173, 1.0
	v_fmac_f32_e32 v173, v175, v173
	v_mul_f32_e32 v175, v174, v173
	v_fma_f32 v227, -v172, v175, v174
	v_fmac_f32_e32 v175, v227, v173
	v_fma_f32 v172, -v172, v175, v174
	v_div_fmas_f32 v175, v172, v173, v175
	v_div_fixup_f32 v218, v175, v153, 1.0
	s_waitcnt vmcnt(0)
	v_pk_add_f32 v[156:157], v[156:157], 1.0 op_sel_hi:[1,0]
	v_pk_add_f32 v[158:159], v[158:159], 1.0 op_sel_hi:[1,0]
	v_pk_add_f32 v[160:161], v[160:161], 1.0 op_sel_hi:[1,0]
	v_pk_add_f32 v[162:163], v[162:163], 1.0 op_sel_hi:[1,0]
	v_pk_add_f32 v[164:165], v[164:165], 1.0 op_sel_hi:[1,0]
	v_pk_add_f32 v[166:167], v[166:167], 1.0 op_sel_hi:[1,0]
	v_pk_add_f32 v[168:169], v[168:169], 1.0 op_sel_hi:[1,0]
	v_pk_add_f32 v[170:171], v[170:171], 1.0 op_sel_hi:[1,0]
	v_and_b32_e32 v144, 16, v230
	v_cmp_ne_u32_e64 s[80:81], 0, v144
	v_mov_b32_e32 v145, 24
	s_nop 0
	v_cndmask_b32_e64 v144, 0, v145, s[80:81]
	global_store_dwordx4 v128, v[124:127], s[8:9]
	global_store_dwordx4 v128, v[104:107], s[8:9] offset:64
	global_store_dwordx4 v128, v[68:71], s[8:9] offset:512
	global_store_dwordx4 v128, v[44:47], s[8:9] offset:576
	v_lshrrev_b32_e32 v139, 1, v128
	v_add_u32_e32 v139, v139, v144
	v_pk_mul_f32 v[124:125], v[124:125], v[204:205] op_sel_hi:[1,0]
	v_pk_mul_f32 v[126:127], v[126:127], v[204:205] op_sel_hi:[1,0]
	v_pk_mul_f32 v[124:125], v[188:189], v[124:125]
	v_pk_mul_f32 v[126:127], v[190:191], v[126:127]
	v_pk_fma_f32 v[124:125], v[156:157], v[124:125], v[232:233]
	v_pk_fma_f32 v[126:127], v[158:159], v[126:127], v[234:235]
	v_cvt_pk_bf16_f32 v124, v124, v125
	v_cvt_pk_bf16_f32 v125, v126, v127
	v_pk_mul_f32 v[104:105], v[104:105], v[204:205] op_sel_hi:[1,0]
	v_pk_mul_f32 v[106:107], v[106:107], v[204:205] op_sel_hi:[1,0]
	v_pk_mul_f32 v[104:105], v[192:193], v[104:105]
	v_pk_mul_f32 v[106:107], v[194:195], v[106:107]
	v_pk_fma_f32 v[104:105], v[160:161], v[104:105], v[236:237]
	v_pk_fma_f32 v[106:107], v[162:163], v[106:107], v[238:239]
	v_cvt_pk_bf16_f32 v104, v104, v105
	v_cvt_pk_bf16_f32 v105, v106, v107
	v_pk_mul_f32 v[68:69], v[68:69], v[204:205] op_sel_hi:[1,0]
	v_pk_mul_f32 v[70:71], v[70:71], v[204:205] op_sel_hi:[1,0]
	v_pk_mul_f32 v[68:69], v[196:197], v[68:69]
	v_pk_mul_f32 v[70:71], v[198:199], v[70:71]
	v_pk_fma_f32 v[68:69], v[164:165], v[68:69], v[240:241]
	v_pk_fma_f32 v[70:71], v[166:167], v[70:71], v[242:243]
	v_cvt_pk_bf16_f32 v68, v68, v69
	v_cvt_pk_bf16_f32 v69, v70, v71
	v_pk_mul_f32 v[44:45], v[44:45], v[204:205] op_sel_hi:[1,0]
	v_pk_mul_f32 v[46:47], v[46:47], v[204:205] op_sel_hi:[1,0]
	v_pk_mul_f32 v[44:45], v[200:201], v[44:45]
	v_pk_mul_f32 v[46:47], v[202:203], v[46:47]
	v_pk_fma_f32 v[44:45], v[168:169], v[44:45], v[244:245]
	v_pk_fma_f32 v[46:47], v[170:171], v[46:47], v[246:247]
	v_cvt_pk_bf16_f32 v44, v44, v45
	v_cvt_pk_bf16_f32 v45, v46, v47
	v_cndmask_b32_e64 v146, v104, v124, s[80:81]
	v_cndmask_b32_e64 v147, v105, v125, s[80:81]
	ds_bpermute_b32 v148, v137, v146
	ds_bpermute_b32 v149, v137, v147
	v_cndmask_b32_e64 v150, v44, v68, s[80:81]
	v_cndmask_b32_e64 v151, v45, v69, s[80:81]
	ds_bpermute_b32 v152, v137, v150
	ds_bpermute_b32 v153, v137, v151
	s_waitcnt lgkmcnt(0)
	v_cndmask_b32_e64 v126, v148, v104, s[80:81]
	v_cndmask_b32_e64 v127, v149, v105, s[80:81]
	v_cndmask_b32_e64 v124, v124, v148, s[80:81]
	v_cndmask_b32_e64 v125, v125, v149, s[80:81]
	global_store_dwordx4 v139, v[124:127], s[74:75]
	v_cndmask_b32_e64 v70, v152, v44, s[80:81]
	v_cndmask_b32_e64 v71, v153, v45, s[80:81]
	v_cndmask_b32_e64 v68, v68, v152, s[80:81]
	v_cndmask_b32_e64 v69, v69, v153, s[80:81]
	global_store_dwordx4 v139, v[68:71], s[74:75] offset:256
	global_store_dwordx4 v129, v[120:123], s[8:9]
	global_store_dwordx4 v129, v[96:99], s[8:9] offset:64
	global_store_dwordx4 v129, v[64:67], s[8:9] offset:512
	global_store_dwordx4 v129, v[36:39], s[8:9] offset:576
	v_lshrrev_b32_e32 v139, 1, v129
	v_add_u32_e32 v139, v139, v144
	v_pk_mul_f32 v[120:121], v[120:121], v[206:207] op_sel_hi:[1,0]
	v_pk_mul_f32 v[122:123], v[122:123], v[206:207] op_sel_hi:[1,0]
	v_pk_mul_f32 v[120:121], v[188:189], v[120:121]
	v_pk_mul_f32 v[122:123], v[190:191], v[122:123]
	v_pk_fma_f32 v[120:121], v[156:157], v[120:121], v[232:233]
	v_pk_fma_f32 v[122:123], v[158:159], v[122:123], v[234:235]
	v_cvt_pk_bf16_f32 v120, v120, v121
	v_cvt_pk_bf16_f32 v121, v122, v123
	v_pk_mul_f32 v[96:97], v[96:97], v[206:207] op_sel_hi:[1,0]
	v_pk_mul_f32 v[98:99], v[98:99], v[206:207] op_sel_hi:[1,0]
	v_pk_mul_f32 v[96:97], v[192:193], v[96:97]
	v_pk_mul_f32 v[98:99], v[194:195], v[98:99]
	v_pk_fma_f32 v[96:97], v[160:161], v[96:97], v[236:237]
	v_pk_fma_f32 v[98:99], v[162:163], v[98:99], v[238:239]
	v_cvt_pk_bf16_f32 v96, v96, v97
	v_cvt_pk_bf16_f32 v97, v98, v99
	v_pk_mul_f32 v[64:65], v[64:65], v[206:207] op_sel_hi:[1,0]
	v_pk_mul_f32 v[66:67], v[66:67], v[206:207] op_sel_hi:[1,0]
	v_pk_mul_f32 v[64:65], v[196:197], v[64:65]
	v_pk_mul_f32 v[66:67], v[198:199], v[66:67]
	v_pk_fma_f32 v[64:65], v[164:165], v[64:65], v[240:241]
	v_pk_fma_f32 v[66:67], v[166:167], v[66:67], v[242:243]
	v_cvt_pk_bf16_f32 v64, v64, v65
	v_cvt_pk_bf16_f32 v65, v66, v67
	v_pk_mul_f32 v[36:37], v[36:37], v[206:207] op_sel_hi:[1,0]
	v_pk_mul_f32 v[38:39], v[38:39], v[206:207] op_sel_hi:[1,0]
	v_pk_mul_f32 v[36:37], v[200:201], v[36:37]
	v_pk_mul_f32 v[38:39], v[202:203], v[38:39]
	v_pk_fma_f32 v[36:37], v[168:169], v[36:37], v[244:245]
	v_pk_fma_f32 v[38:39], v[170:171], v[38:39], v[246:247]
	v_cvt_pk_bf16_f32 v36, v36, v37
	v_cvt_pk_bf16_f32 v37, v38, v39
	v_cndmask_b32_e64 v146, v96, v120, s[80:81]
	v_cndmask_b32_e64 v147, v97, v121, s[80:81]
	ds_bpermute_b32 v148, v137, v146
	ds_bpermute_b32 v149, v137, v147
	v_cndmask_b32_e64 v150, v36, v64, s[80:81]
	v_cndmask_b32_e64 v151, v37, v65, s[80:81]
	ds_bpermute_b32 v152, v137, v150
	ds_bpermute_b32 v153, v137, v151
	s_waitcnt lgkmcnt(0)
	v_cndmask_b32_e64 v122, v148, v96, s[80:81]
	v_cndmask_b32_e64 v123, v149, v97, s[80:81]
	v_cndmask_b32_e64 v120, v120, v148, s[80:81]
	v_cndmask_b32_e64 v121, v121, v149, s[80:81]
	global_store_dwordx4 v139, v[120:123], s[74:75]
	v_cndmask_b32_e64 v66, v152, v36, s[80:81]
	v_cndmask_b32_e64 v67, v153, v37, s[80:81]
	v_cndmask_b32_e64 v64, v64, v152, s[80:81]
	v_cndmask_b32_e64 v65, v65, v153, s[80:81]
	global_store_dwordx4 v139, v[64:67], s[74:75] offset:256
	global_store_dwordx4 v130, v[116:119], s[8:9]
	global_store_dwordx4 v130, v[88:91], s[8:9] offset:64
	global_store_dwordx4 v130, v[52:55], s[8:9] offset:512
	global_store_dwordx4 v130, v[28:31], s[8:9] offset:576
	v_lshrrev_b32_e32 v139, 1, v130
	v_add_u32_e32 v139, v139, v144
	v_pk_mul_f32 v[116:117], v[116:117], v[208:209] op_sel_hi:[1,0]
	v_pk_mul_f32 v[118:119], v[118:119], v[208:209] op_sel_hi:[1,0]
	v_pk_mul_f32 v[116:117], v[188:189], v[116:117]
	v_pk_mul_f32 v[118:119], v[190:191], v[118:119]
	v_pk_fma_f32 v[116:117], v[156:157], v[116:117], v[232:233]
	v_pk_fma_f32 v[118:119], v[158:159], v[118:119], v[234:235]
	v_cvt_pk_bf16_f32 v116, v116, v117
	v_cvt_pk_bf16_f32 v117, v118, v119
	v_pk_mul_f32 v[88:89], v[88:89], v[208:209] op_sel_hi:[1,0]
	v_pk_mul_f32 v[90:91], v[90:91], v[208:209] op_sel_hi:[1,0]
	v_pk_mul_f32 v[88:89], v[192:193], v[88:89]
	v_pk_mul_f32 v[90:91], v[194:195], v[90:91]
	v_pk_fma_f32 v[88:89], v[160:161], v[88:89], v[236:237]
	v_pk_fma_f32 v[90:91], v[162:163], v[90:91], v[238:239]
	v_cvt_pk_bf16_f32 v88, v88, v89
	v_cvt_pk_bf16_f32 v89, v90, v91
	v_pk_mul_f32 v[52:53], v[52:53], v[208:209] op_sel_hi:[1,0]
	v_pk_mul_f32 v[54:55], v[54:55], v[208:209] op_sel_hi:[1,0]
	v_pk_mul_f32 v[52:53], v[196:197], v[52:53]
	v_pk_mul_f32 v[54:55], v[198:199], v[54:55]
	v_pk_fma_f32 v[52:53], v[164:165], v[52:53], v[240:241]
	v_pk_fma_f32 v[54:55], v[166:167], v[54:55], v[242:243]
	v_cvt_pk_bf16_f32 v52, v52, v53
	v_cvt_pk_bf16_f32 v53, v54, v55
	v_pk_mul_f32 v[28:29], v[28:29], v[208:209] op_sel_hi:[1,0]
	v_pk_mul_f32 v[30:31], v[30:31], v[208:209] op_sel_hi:[1,0]
	v_pk_mul_f32 v[28:29], v[200:201], v[28:29]
	v_pk_mul_f32 v[30:31], v[202:203], v[30:31]
	v_pk_fma_f32 v[28:29], v[168:169], v[28:29], v[244:245]
	v_pk_fma_f32 v[30:31], v[170:171], v[30:31], v[246:247]
	v_cvt_pk_bf16_f32 v28, v28, v29
	v_cvt_pk_bf16_f32 v29, v30, v31
	v_cndmask_b32_e64 v146, v88, v116, s[80:81]
	v_cndmask_b32_e64 v147, v89, v117, s[80:81]
	ds_bpermute_b32 v148, v137, v146
	ds_bpermute_b32 v149, v137, v147
	v_cndmask_b32_e64 v150, v28, v52, s[80:81]
	v_cndmask_b32_e64 v151, v29, v53, s[80:81]
	ds_bpermute_b32 v152, v137, v150
	ds_bpermute_b32 v153, v137, v151
	s_waitcnt lgkmcnt(0)
	v_cndmask_b32_e64 v118, v148, v88, s[80:81]
	v_cndmask_b32_e64 v119, v149, v89, s[80:81]
	v_cndmask_b32_e64 v116, v116, v148, s[80:81]
	v_cndmask_b32_e64 v117, v117, v149, s[80:81]
	global_store_dwordx4 v139, v[116:119], s[74:75]
	v_cndmask_b32_e64 v54, v152, v28, s[80:81]
	v_cndmask_b32_e64 v55, v153, v29, s[80:81]
	v_cndmask_b32_e64 v52, v52, v152, s[80:81]
	v_cndmask_b32_e64 v53, v53, v153, s[80:81]
	global_store_dwordx4 v139, v[52:55], s[74:75] offset:256
	global_store_dwordx4 v131, v[112:115], s[8:9]
	global_store_dwordx4 v131, v[80:83], s[8:9] offset:64
	global_store_dwordx4 v131, v[48:51], s[8:9] offset:512
	global_store_dwordx4 v131, v[20:23], s[8:9] offset:576
	v_lshrrev_b32_e32 v139, 1, v131
	v_add_u32_e32 v139, v139, v144
	v_pk_mul_f32 v[112:113], v[112:113], v[210:211] op_sel_hi:[1,0]
	v_pk_mul_f32 v[114:115], v[114:115], v[210:211] op_sel_hi:[1,0]
	v_pk_mul_f32 v[112:113], v[188:189], v[112:113]
	v_pk_mul_f32 v[114:115], v[190:191], v[114:115]
	v_pk_fma_f32 v[112:113], v[156:157], v[112:113], v[232:233]
	v_pk_fma_f32 v[114:115], v[158:159], v[114:115], v[234:235]
	v_cvt_pk_bf16_f32 v112, v112, v113
	v_cvt_pk_bf16_f32 v113, v114, v115
	v_pk_mul_f32 v[80:81], v[80:81], v[210:211] op_sel_hi:[1,0]
	v_pk_mul_f32 v[82:83], v[82:83], v[210:211] op_sel_hi:[1,0]
	v_pk_mul_f32 v[80:81], v[192:193], v[80:81]
	v_pk_mul_f32 v[82:83], v[194:195], v[82:83]
	v_pk_fma_f32 v[80:81], v[160:161], v[80:81], v[236:237]
	v_pk_fma_f32 v[82:83], v[162:163], v[82:83], v[238:239]
	v_cvt_pk_bf16_f32 v80, v80, v81
	v_cvt_pk_bf16_f32 v81, v82, v83
	v_pk_mul_f32 v[48:49], v[48:49], v[210:211] op_sel_hi:[1,0]
	v_pk_mul_f32 v[50:51], v[50:51], v[210:211] op_sel_hi:[1,0]
	v_pk_mul_f32 v[48:49], v[196:197], v[48:49]
	v_pk_mul_f32 v[50:51], v[198:199], v[50:51]
	v_pk_fma_f32 v[48:49], v[164:165], v[48:49], v[240:241]
	v_pk_fma_f32 v[50:51], v[166:167], v[50:51], v[242:243]
	v_cvt_pk_bf16_f32 v48, v48, v49
	v_cvt_pk_bf16_f32 v49, v50, v51
	v_pk_mul_f32 v[20:21], v[20:21], v[210:211] op_sel_hi:[1,0]
	v_pk_mul_f32 v[22:23], v[22:23], v[210:211] op_sel_hi:[1,0]
	v_pk_mul_f32 v[20:21], v[200:201], v[20:21]
	v_pk_mul_f32 v[22:23], v[202:203], v[22:23]
	v_pk_fma_f32 v[20:21], v[168:169], v[20:21], v[244:245]
	v_pk_fma_f32 v[22:23], v[170:171], v[22:23], v[246:247]
	v_cvt_pk_bf16_f32 v20, v20, v21
	v_cvt_pk_bf16_f32 v21, v22, v23
	v_cndmask_b32_e64 v146, v80, v112, s[80:81]
	v_cndmask_b32_e64 v147, v81, v113, s[80:81]
	ds_bpermute_b32 v148, v137, v146
	ds_bpermute_b32 v149, v137, v147
	v_cndmask_b32_e64 v150, v20, v48, s[80:81]
	v_cndmask_b32_e64 v151, v21, v49, s[80:81]
	ds_bpermute_b32 v152, v137, v150
	ds_bpermute_b32 v153, v137, v151
	s_waitcnt lgkmcnt(0)
	v_cndmask_b32_e64 v114, v148, v80, s[80:81]
	v_cndmask_b32_e64 v115, v149, v81, s[80:81]
	v_cndmask_b32_e64 v112, v112, v148, s[80:81]
	v_cndmask_b32_e64 v113, v113, v149, s[80:81]
	global_store_dwordx4 v139, v[112:115], s[74:75]
	v_cndmask_b32_e64 v50, v152, v20, s[80:81]
	v_cndmask_b32_e64 v51, v153, v21, s[80:81]
	v_cndmask_b32_e64 v48, v48, v152, s[80:81]
	v_cndmask_b32_e64 v49, v49, v153, s[80:81]
	global_store_dwordx4 v139, v[48:51], s[74:75] offset:256
	global_store_dwordx4 v132, v[108:111], s[8:9]
	global_store_dwordx4 v132, v[76:79], s[8:9] offset:64
	global_store_dwordx4 v132, v[40:43], s[8:9] offset:512
	global_store_dwordx4 v132, v[12:15], s[8:9] offset:576
	v_lshrrev_b32_e32 v139, 1, v132
	v_add_u32_e32 v139, v139, v144
	v_pk_mul_f32 v[108:109], v[108:109], v[212:213] op_sel_hi:[1,0]
	v_pk_mul_f32 v[110:111], v[110:111], v[212:213] op_sel_hi:[1,0]
	v_pk_mul_f32 v[108:109], v[188:189], v[108:109]
	v_pk_mul_f32 v[110:111], v[190:191], v[110:111]
	v_pk_fma_f32 v[108:109], v[156:157], v[108:109], v[232:233]
	v_pk_fma_f32 v[110:111], v[158:159], v[110:111], v[234:235]
	v_cvt_pk_bf16_f32 v108, v108, v109
	v_cvt_pk_bf16_f32 v109, v110, v111
	v_pk_mul_f32 v[76:77], v[76:77], v[212:213] op_sel_hi:[1,0]
	v_pk_mul_f32 v[78:79], v[78:79], v[212:213] op_sel_hi:[1,0]
	v_pk_mul_f32 v[76:77], v[192:193], v[76:77]
	v_pk_mul_f32 v[78:79], v[194:195], v[78:79]
	v_pk_fma_f32 v[76:77], v[160:161], v[76:77], v[236:237]
	v_pk_fma_f32 v[78:79], v[162:163], v[78:79], v[238:239]
	v_cvt_pk_bf16_f32 v76, v76, v77
	v_cvt_pk_bf16_f32 v77, v78, v79
	v_pk_mul_f32 v[40:41], v[40:41], v[212:213] op_sel_hi:[1,0]
	v_pk_mul_f32 v[42:43], v[42:43], v[212:213] op_sel_hi:[1,0]
	v_pk_mul_f32 v[40:41], v[196:197], v[40:41]
	v_pk_mul_f32 v[42:43], v[198:199], v[42:43]
	v_pk_fma_f32 v[40:41], v[164:165], v[40:41], v[240:241]
	v_pk_fma_f32 v[42:43], v[166:167], v[42:43], v[242:243]
	v_cvt_pk_bf16_f32 v40, v40, v41
	v_cvt_pk_bf16_f32 v41, v42, v43
	v_pk_mul_f32 v[12:13], v[12:13], v[212:213] op_sel_hi:[1,0]
	v_pk_mul_f32 v[14:15], v[14:15], v[212:213] op_sel_hi:[1,0]
	v_pk_mul_f32 v[12:13], v[200:201], v[12:13]
	v_pk_mul_f32 v[14:15], v[202:203], v[14:15]
	v_pk_fma_f32 v[12:13], v[168:169], v[12:13], v[244:245]
	v_pk_fma_f32 v[14:15], v[170:171], v[14:15], v[246:247]
	v_cvt_pk_bf16_f32 v12, v12, v13
	v_cvt_pk_bf16_f32 v13, v14, v15
	v_cndmask_b32_e64 v146, v76, v108, s[80:81]
	v_cndmask_b32_e64 v147, v77, v109, s[80:81]
	ds_bpermute_b32 v148, v137, v146
	ds_bpermute_b32 v149, v137, v147
	v_cndmask_b32_e64 v150, v12, v40, s[80:81]
	v_cndmask_b32_e64 v151, v13, v41, s[80:81]
	ds_bpermute_b32 v152, v137, v150
	ds_bpermute_b32 v153, v137, v151
	s_waitcnt lgkmcnt(0)
	v_cndmask_b32_e64 v110, v148, v76, s[80:81]
	v_cndmask_b32_e64 v111, v149, v77, s[80:81]
	v_cndmask_b32_e64 v108, v108, v148, s[80:81]
	v_cndmask_b32_e64 v109, v109, v149, s[80:81]
	global_store_dwordx4 v139, v[108:111], s[74:75]
	v_cndmask_b32_e64 v42, v152, v12, s[80:81]
	v_cndmask_b32_e64 v43, v153, v13, s[80:81]
	v_cndmask_b32_e64 v40, v40, v152, s[80:81]
	v_cndmask_b32_e64 v41, v41, v153, s[80:81]
	global_store_dwordx4 v139, v[40:43], s[74:75] offset:256
	global_store_dwordx4 v133, v[100:103], s[8:9]
	global_store_dwordx4 v133, v[72:75], s[8:9] offset:64
	global_store_dwordx4 v133, v[32:35], s[8:9] offset:512
	global_store_dwordx4 v133, v[8:11], s[8:9] offset:576
	v_lshrrev_b32_e32 v139, 1, v133
	v_add_u32_e32 v139, v139, v144
	v_pk_mul_f32 v[100:101], v[100:101], v[214:215] op_sel_hi:[1,0]
	v_pk_mul_f32 v[102:103], v[102:103], v[214:215] op_sel_hi:[1,0]
	v_pk_mul_f32 v[100:101], v[188:189], v[100:101]
	v_pk_mul_f32 v[102:103], v[190:191], v[102:103]
	v_pk_fma_f32 v[100:101], v[156:157], v[100:101], v[232:233]
	v_pk_fma_f32 v[102:103], v[158:159], v[102:103], v[234:235]
	v_cvt_pk_bf16_f32 v100, v100, v101
	v_cvt_pk_bf16_f32 v101, v102, v103
	v_pk_mul_f32 v[72:73], v[72:73], v[214:215] op_sel_hi:[1,0]
	v_pk_mul_f32 v[74:75], v[74:75], v[214:215] op_sel_hi:[1,0]
	v_pk_mul_f32 v[72:73], v[192:193], v[72:73]
	v_pk_mul_f32 v[74:75], v[194:195], v[74:75]
	v_pk_fma_f32 v[72:73], v[160:161], v[72:73], v[236:237]
	v_pk_fma_f32 v[74:75], v[162:163], v[74:75], v[238:239]
	v_cvt_pk_bf16_f32 v72, v72, v73
	v_cvt_pk_bf16_f32 v73, v74, v75
	v_pk_mul_f32 v[32:33], v[32:33], v[214:215] op_sel_hi:[1,0]
	v_pk_mul_f32 v[34:35], v[34:35], v[214:215] op_sel_hi:[1,0]
	v_pk_mul_f32 v[32:33], v[196:197], v[32:33]
	v_pk_mul_f32 v[34:35], v[198:199], v[34:35]
	v_pk_fma_f32 v[32:33], v[164:165], v[32:33], v[240:241]
	v_pk_fma_f32 v[34:35], v[166:167], v[34:35], v[242:243]
	v_cvt_pk_bf16_f32 v32, v32, v33
	v_cvt_pk_bf16_f32 v33, v34, v35
	v_pk_mul_f32 v[8:9], v[8:9], v[214:215] op_sel_hi:[1,0]
	v_pk_mul_f32 v[10:11], v[10:11], v[214:215] op_sel_hi:[1,0]
	v_pk_mul_f32 v[8:9], v[200:201], v[8:9]
	v_pk_mul_f32 v[10:11], v[202:203], v[10:11]
	v_pk_fma_f32 v[8:9], v[168:169], v[8:9], v[244:245]
	v_pk_fma_f32 v[10:11], v[170:171], v[10:11], v[246:247]
	v_cvt_pk_bf16_f32 v8, v8, v9
	v_cvt_pk_bf16_f32 v9, v10, v11
	v_cndmask_b32_e64 v146, v72, v100, s[80:81]
	v_cndmask_b32_e64 v147, v73, v101, s[80:81]
	ds_bpermute_b32 v148, v137, v146
	ds_bpermute_b32 v149, v137, v147
	v_cndmask_b32_e64 v150, v8, v32, s[80:81]
	v_cndmask_b32_e64 v151, v9, v33, s[80:81]
	ds_bpermute_b32 v152, v137, v150
	ds_bpermute_b32 v153, v137, v151
	s_waitcnt lgkmcnt(0)
	v_cndmask_b32_e64 v102, v148, v72, s[80:81]
	v_cndmask_b32_e64 v103, v149, v73, s[80:81]
	v_cndmask_b32_e64 v100, v100, v148, s[80:81]
	v_cndmask_b32_e64 v101, v101, v149, s[80:81]
	global_store_dwordx4 v139, v[100:103], s[74:75]
	v_cndmask_b32_e64 v34, v152, v8, s[80:81]
	v_cndmask_b32_e64 v35, v153, v9, s[80:81]
	v_cndmask_b32_e64 v32, v32, v152, s[80:81]
	v_cndmask_b32_e64 v33, v33, v153, s[80:81]
	global_store_dwordx4 v139, v[32:35], s[74:75] offset:256
	global_store_dwordx4 v134, v[92:95], s[8:9]
	global_store_dwordx4 v134, v[60:63], s[8:9] offset:64
	global_store_dwordx4 v134, v[24:27], s[8:9] offset:512
	global_store_dwordx4 v134, v[4:7], s[8:9] offset:576
	v_lshrrev_b32_e32 v139, 1, v134
	v_add_u32_e32 v139, v139, v144
	v_pk_mul_f32 v[92:93], v[92:93], v[216:217] op_sel_hi:[1,0]
	v_pk_mul_f32 v[94:95], v[94:95], v[216:217] op_sel_hi:[1,0]
	v_pk_mul_f32 v[92:93], v[188:189], v[92:93]
	v_pk_mul_f32 v[94:95], v[190:191], v[94:95]
	v_pk_fma_f32 v[92:93], v[156:157], v[92:93], v[232:233]
	v_pk_fma_f32 v[94:95], v[158:159], v[94:95], v[234:235]
	v_cvt_pk_bf16_f32 v92, v92, v93
	v_cvt_pk_bf16_f32 v93, v94, v95
	v_pk_mul_f32 v[60:61], v[60:61], v[216:217] op_sel_hi:[1,0]
	v_pk_mul_f32 v[62:63], v[62:63], v[216:217] op_sel_hi:[1,0]
	v_pk_mul_f32 v[60:61], v[192:193], v[60:61]
	v_pk_mul_f32 v[62:63], v[194:195], v[62:63]
	v_pk_fma_f32 v[60:61], v[160:161], v[60:61], v[236:237]
	v_pk_fma_f32 v[62:63], v[162:163], v[62:63], v[238:239]
	v_cvt_pk_bf16_f32 v60, v60, v61
	v_cvt_pk_bf16_f32 v61, v62, v63
	v_pk_mul_f32 v[24:25], v[24:25], v[216:217] op_sel_hi:[1,0]
	v_pk_mul_f32 v[26:27], v[26:27], v[216:217] op_sel_hi:[1,0]
	v_pk_mul_f32 v[24:25], v[196:197], v[24:25]
	v_pk_mul_f32 v[26:27], v[198:199], v[26:27]
	v_pk_fma_f32 v[24:25], v[164:165], v[24:25], v[240:241]
	v_pk_fma_f32 v[26:27], v[166:167], v[26:27], v[242:243]
	v_cvt_pk_bf16_f32 v24, v24, v25
	v_cvt_pk_bf16_f32 v25, v26, v27
	v_pk_mul_f32 v[4:5], v[4:5], v[216:217] op_sel_hi:[1,0]
	v_pk_mul_f32 v[6:7], v[6:7], v[216:217] op_sel_hi:[1,0]
	v_pk_mul_f32 v[4:5], v[200:201], v[4:5]
	v_pk_mul_f32 v[6:7], v[202:203], v[6:7]
	v_pk_fma_f32 v[4:5], v[168:169], v[4:5], v[244:245]
	v_pk_fma_f32 v[6:7], v[170:171], v[6:7], v[246:247]
	v_cvt_pk_bf16_f32 v4, v4, v5
	v_cvt_pk_bf16_f32 v5, v6, v7
	v_cndmask_b32_e64 v146, v60, v92, s[80:81]
	v_cndmask_b32_e64 v147, v61, v93, s[80:81]
	ds_bpermute_b32 v148, v137, v146
	ds_bpermute_b32 v149, v137, v147
	v_cndmask_b32_e64 v150, v4, v24, s[80:81]
	v_cndmask_b32_e64 v151, v5, v25, s[80:81]
	ds_bpermute_b32 v152, v137, v150
	ds_bpermute_b32 v153, v137, v151
	s_waitcnt lgkmcnt(0)
	v_cndmask_b32_e64 v94, v148, v60, s[80:81]
	v_cndmask_b32_e64 v95, v149, v61, s[80:81]
	v_cndmask_b32_e64 v92, v92, v148, s[80:81]
	v_cndmask_b32_e64 v93, v93, v149, s[80:81]
	global_store_dwordx4 v139, v[92:95], s[74:75]
	v_cndmask_b32_e64 v26, v152, v4, s[80:81]
	v_cndmask_b32_e64 v27, v153, v5, s[80:81]
	v_cndmask_b32_e64 v24, v24, v152, s[80:81]
	v_cndmask_b32_e64 v25, v25, v153, s[80:81]
	global_store_dwordx4 v139, v[24:27], s[74:75] offset:256
	global_store_dwordx4 v135, v[84:87], s[8:9]
	global_store_dwordx4 v135, v[56:59], s[8:9] offset:64
	global_store_dwordx4 v135, v[16:19], s[8:9] offset:512
	global_store_dwordx4 v135, v[0:3], s[8:9] offset:576
	v_lshrrev_b32_e32 v139, 1, v135
	v_add_u32_e32 v139, v139, v144
	v_pk_mul_f32 v[84:85], v[84:85], v[218:219] op_sel_hi:[1,0]
	v_pk_mul_f32 v[86:87], v[86:87], v[218:219] op_sel_hi:[1,0]
	v_pk_mul_f32 v[84:85], v[188:189], v[84:85]
	v_pk_mul_f32 v[86:87], v[190:191], v[86:87]
	v_pk_fma_f32 v[84:85], v[156:157], v[84:85], v[232:233]
	v_pk_fma_f32 v[86:87], v[158:159], v[86:87], v[234:235]
	v_cvt_pk_bf16_f32 v84, v84, v85
	v_cvt_pk_bf16_f32 v85, v86, v87
	v_pk_mul_f32 v[56:57], v[56:57], v[218:219] op_sel_hi:[1,0]
	v_pk_mul_f32 v[58:59], v[58:59], v[218:219] op_sel_hi:[1,0]
	v_pk_mul_f32 v[56:57], v[192:193], v[56:57]
	v_pk_mul_f32 v[58:59], v[194:195], v[58:59]
	v_pk_fma_f32 v[56:57], v[160:161], v[56:57], v[236:237]
	v_pk_fma_f32 v[58:59], v[162:163], v[58:59], v[238:239]
	v_cvt_pk_bf16_f32 v56, v56, v57
	v_cvt_pk_bf16_f32 v57, v58, v59
	v_pk_mul_f32 v[16:17], v[16:17], v[218:219] op_sel_hi:[1,0]
	v_pk_mul_f32 v[18:19], v[18:19], v[218:219] op_sel_hi:[1,0]
	v_pk_mul_f32 v[16:17], v[196:197], v[16:17]
	v_pk_mul_f32 v[18:19], v[198:199], v[18:19]
	v_pk_fma_f32 v[16:17], v[164:165], v[16:17], v[240:241]
	v_pk_fma_f32 v[18:19], v[166:167], v[18:19], v[242:243]
	v_cvt_pk_bf16_f32 v16, v16, v17
	v_cvt_pk_bf16_f32 v17, v18, v19
	v_pk_mul_f32 v[0:1], v[0:1], v[218:219] op_sel_hi:[1,0]
	v_pk_mul_f32 v[2:3], v[2:3], v[218:219] op_sel_hi:[1,0]
	v_pk_mul_f32 v[0:1], v[200:201], v[0:1]
	v_pk_mul_f32 v[2:3], v[202:203], v[2:3]
	v_pk_fma_f32 v[0:1], v[168:169], v[0:1], v[244:245]
	v_pk_fma_f32 v[2:3], v[170:171], v[2:3], v[246:247]
	v_cvt_pk_bf16_f32 v0, v0, v1
	v_cvt_pk_bf16_f32 v1, v2, v3
	v_cndmask_b32_e64 v146, v56, v84, s[80:81]
	v_cndmask_b32_e64 v147, v57, v85, s[80:81]
	ds_bpermute_b32 v148, v137, v146
	ds_bpermute_b32 v149, v137, v147
	v_cndmask_b32_e64 v150, v0, v16, s[80:81]
	v_cndmask_b32_e64 v151, v1, v17, s[80:81]
	ds_bpermute_b32 v152, v137, v150
	ds_bpermute_b32 v153, v137, v151
	s_waitcnt lgkmcnt(0)
	v_cndmask_b32_e64 v86, v148, v56, s[80:81]
	v_cndmask_b32_e64 v87, v149, v57, s[80:81]
	v_cndmask_b32_e64 v84, v84, v148, s[80:81]
	v_cndmask_b32_e64 v85, v85, v149, s[80:81]
	global_store_dwordx4 v139, v[84:87], s[74:75]
	v_cndmask_b32_e64 v18, v152, v0, s[80:81]
	v_cndmask_b32_e64 v19, v153, v1, s[80:81]
	v_cndmask_b32_e64 v16, v16, v152, s[80:81]
	v_cndmask_b32_e64 v17, v17, v153, s[80:81]
	global_store_dwordx4 v139, v[16:19], s[74:75] offset:256
	s_mov_b64 s[34:35], -1
	s_and_b64 vcc, exec, s[4:5]
	s_cbranch_vccnz .LBB0_346
	s_andn2_b64 vcc, exec, s[14:15]
	s_cbranch_vccnz .LBB0_345
	s_barrier
	s_branch .LBB0_345

.LBB0_1203:
	s_mov_b32 s40, s38
	s_mov_b32 s41, s39
	v_lshl_add_u32 v128, s38, 8, v206
	v_lshl_or_b32 v136, s39, 8, v208
	s_load_dwordx2 s[42:43], s[92:93], 0xa8
	s_load_dwordx2 s[44:45], s[92:93], 0xd8
	s_ashr_i32 s2, s38, 4
	v_lshlrev_b32_e32 v136, 2, v136
	s_mul_hi_i32 s15, s2, 0x9000
	s_mul_i32 s2, s2, 0x9000
	v_lshl_add_u32 v128, v128, 12, v136
	s_add_u32 s38, s58, s2
	s_addc_u32 s39, s59, s15
	v_add_u32_e32 v129, 0x10000, v128
	v_add_u32_e32 v130, 0x20000, v128
	v_add_u32_e32 v131, 0x30000, v128
	v_add_u32_e32 v132, 0x80000, v128
	v_add_u32_e32 v133, 0x90000, v128
	v_add_u32_e32 v134, 0xa0000, v128
	v_add_u32_e32 v135, 0xb0000, v128
	v_and_b32_e32 v137, 63, v230
	v_xor_b32_e32 v138, 32, v137
	v_xor_b32_e32 v137, 16, v137
	v_lshlrev_b32_e32 v138, 2, v138
	v_lshlrev_b32_e32 v137, 2, v137
	global_load_dwordx4 v[140:143], v136, s[38:39]
	global_load_dwordx4 v[144:147], v136, s[38:39] offset:64
	global_load_dwordx4 v[148:151], v136, s[38:39] offset:512
	global_load_dwordx4 v[152:155], v136, s[38:39] offset:576
	global_load_dwordx4 v[180:183], v128, s[8:9]
	global_load_dwordx4 v[184:187], v128, s[8:9] offset:64
	global_load_dwordx4 v[188:191], v128, s[8:9] offset:512
	global_load_dwordx4 v[192:195], v128, s[8:9] offset:576
	global_load_dwordx4 v[196:199], v129, s[8:9]
	global_load_dwordx4 v[200:203], v129, s[8:9] offset:64
	global_load_dwordx4 v[212:215], v129, s[8:9] offset:512
	global_load_dwordx4 v[216:219], v129, s[8:9] offset:576
	global_load_dwordx4 v[220:223], v130, s[8:9]
	global_load_dwordx4 v[224:227], v130, s[8:9] offset:64
	global_load_dwordx4 v[232:235], v130, s[8:9] offset:512
	global_load_dwordx4 v[236:239], v130, s[8:9] offset:576
	global_load_dwordx4 v[240:243], v131, s[8:9]
	global_load_dwordx4 v[244:247], v131, s[8:9] offset:64
	global_load_dwordx4 v[156:159], v131, s[8:9] offset:512
	global_load_dwordx4 v[160:163], v131, s[8:9] offset:576
	s_waitcnt lgkmcnt(0)
	s_add_u32 s66, s44, 0x3010000
	s_addc_u32 s67, s45, 0
	s_add_u32 s66, s66, s2
	s_addc_u32 s67, s67, s15
	s_add_u32 s70, s66, 0x7000
	s_addc_u32 s71, s67, 0
	s_add_u32 s72, s66, 0x6000
	s_addc_u32 s73, s67, 0
	s_add_u32 s68, s44, 0x86a0000
	s_addc_u32 s69, s45, 0
	s_add_u32 s44, s44, 0x32a0000
	s_addc_u32 s45, s45, 0
	s_add_u32 s46, s44, 0x100000
	s_addc_u32 s47, s45, 0
	s_waitcnt vmcnt(8)
	v_pk_fma_f32 v[124:125], v[124:125], v[140:141], v[180:181]
	v_pk_fma_f32 v[126:127], v[126:127], v[142:143], v[182:183]
	v_pk_mul_f32 v[248:249], v[124:125], v[124:125]
	v_pk_fma_f32 v[248:249], v[126:127], v[126:127], v[248:249]
	v_pk_fma_f32 v[100:101], v[100:101], v[144:145], v[184:185]
	v_pk_fma_f32 v[102:103], v[102:103], v[146:147], v[186:187]
	v_pk_fma_f32 v[248:249], v[100:101], v[100:101], v[248:249]
	v_pk_fma_f32 v[248:249], v[102:103], v[102:103], v[248:249]
	v_pk_fma_f32 v[68:69], v[68:69], v[148:149], v[188:189]
	v_pk_fma_f32 v[70:71], v[70:71], v[150:151], v[190:191]
	v_pk_fma_f32 v[248:249], v[68:69], v[68:69], v[248:249]
	v_pk_fma_f32 v[248:249], v[70:71], v[70:71], v[248:249]
	v_pk_fma_f32 v[44:45], v[44:45], v[152:153], v[192:193]
	v_pk_fma_f32 v[46:47], v[46:47], v[154:155], v[194:195]
	v_pk_fma_f32 v[248:249], v[44:45], v[44:45], v[248:249]
	v_pk_fma_f32 v[248:249], v[46:47], v[46:47], v[248:249]
	s_nop 0
	v_add_f32_e32 v164, v248, v249
	v_pk_fma_f32 v[120:121], v[120:121], v[140:141], v[196:197]
	v_pk_fma_f32 v[122:123], v[122:123], v[142:143], v[198:199]
	v_pk_mul_f32 v[248:249], v[120:121], v[120:121]
	v_pk_fma_f32 v[248:249], v[122:123], v[122:123], v[248:249]
	v_pk_fma_f32 v[96:97], v[96:97], v[144:145], v[200:201]
	v_pk_fma_f32 v[98:99], v[98:99], v[146:147], v[202:203]
	v_pk_fma_f32 v[248:249], v[96:97], v[96:97], v[248:249]
	v_pk_fma_f32 v[248:249], v[98:99], v[98:99], v[248:249]
	v_pk_fma_f32 v[64:65], v[64:65], v[148:149], v[212:213]
	v_pk_fma_f32 v[66:67], v[66:67], v[150:151], v[214:215]
	v_pk_fma_f32 v[248:249], v[64:65], v[64:65], v[248:249]
	v_pk_fma_f32 v[248:249], v[66:67], v[66:67], v[248:249]
	v_pk_fma_f32 v[36:37], v[36:37], v[152:153], v[216:217]
	v_pk_fma_f32 v[38:39], v[38:39], v[154:155], v[218:219]
	v_pk_fma_f32 v[248:249], v[36:37], v[36:37], v[248:249]
	v_pk_fma_f32 v[248:249], v[38:39], v[38:39], v[248:249]
	s_nop 0
	v_add_f32_e32 v165, v248, v249
	s_nop 1
	global_load_dwordx4 v[180:183], v132, s[8:9]
	global_load_dwordx4 v[184:187], v132, s[8:9] offset:64
	global_load_dwordx4 v[188:191], v132, s[8:9] offset:512
	global_load_dwordx4 v[192:195], v132, s[8:9] offset:576
	global_load_dwordx4 v[196:199], v133, s[8:9]
	global_load_dwordx4 v[200:203], v133, s[8:9] offset:64
	global_load_dwordx4 v[212:215], v133, s[8:9] offset:512
	global_load_dwordx4 v[216:219], v133, s[8:9] offset:576
	s_waitcnt vmcnt(8)
	v_pk_fma_f32 v[116:117], v[116:117], v[140:141], v[220:221]
	v_pk_fma_f32 v[118:119], v[118:119], v[142:143], v[222:223]
	v_pk_mul_f32 v[248:249], v[116:117], v[116:117]
	v_pk_fma_f32 v[248:249], v[118:119], v[118:119], v[248:249]
	v_pk_fma_f32 v[88:89], v[88:89], v[144:145], v[224:225]
	v_pk_fma_f32 v[90:91], v[90:91], v[146:147], v[226:227]
	v_pk_fma_f32 v[248:249], v[88:89], v[88:89], v[248:249]
	v_pk_fma_f32 v[248:249], v[90:91], v[90:91], v[248:249]
	v_pk_fma_f32 v[52:53], v[52:53], v[148:149], v[232:233]
	v_pk_fma_f32 v[54:55], v[54:55], v[150:151], v[234:235]
	v_pk_fma_f32 v[248:249], v[52:53], v[52:53], v[248:249]
	v_pk_fma_f32 v[248:249], v[54:55], v[54:55], v[248:249]
	v_pk_fma_f32 v[28:29], v[28:29], v[152:153], v[236:237]
	v_pk_fma_f32 v[30:31], v[30:31], v[154:155], v[238:239]
	v_pk_fma_f32 v[248:249], v[28:29], v[28:29], v[248:249]
	v_pk_fma_f32 v[248:249], v[30:31], v[30:31], v[248:249]
	s_nop 0
	v_add_f32_e32 v166, v248, v249
	v_pk_fma_f32 v[112:113], v[112:113], v[140:141], v[240:241]
	v_pk_fma_f32 v[114:115], v[114:115], v[142:143], v[242:243]
	v_pk_mul_f32 v[248:249], v[112:113], v[112:113]
	v_pk_fma_f32 v[248:249], v[114:115], v[114:115], v[248:249]
	v_pk_fma_f32 v[80:81], v[80:81], v[144:145], v[244:245]
	v_pk_fma_f32 v[82:83], v[82:83], v[146:147], v[246:247]
	v_pk_fma_f32 v[248:249], v[80:81], v[80:81], v[248:249]
	v_pk_fma_f32 v[248:249], v[82:83], v[82:83], v[248:249]
	v_pk_fma_f32 v[48:49], v[48:49], v[148:149], v[156:157]
	v_pk_fma_f32 v[50:51], v[50:51], v[150:151], v[158:159]
	v_pk_fma_f32 v[248:249], v[48:49], v[48:49], v[248:249]
	v_pk_fma_f32 v[248:249], v[50:51], v[50:51], v[248:249]
	v_pk_fma_f32 v[20:21], v[20:21], v[152:153], v[160:161]
	v_pk_fma_f32 v[22:23], v[22:23], v[154:155], v[162:163]
	v_pk_fma_f32 v[248:249], v[20:21], v[20:21], v[248:249]
	v_pk_fma_f32 v[248:249], v[22:23], v[22:23], v[248:249]
	s_nop 0
	v_add_f32_e32 v167, v248, v249
	s_nop 1
	global_load_dwordx4 v[220:223], v134, s[8:9]
	global_load_dwordx4 v[224:227], v134, s[8:9] offset:64
	global_load_dwordx4 v[232:235], v134, s[8:9] offset:512
	global_load_dwordx4 v[236:239], v134, s[8:9] offset:576
	global_load_dwordx4 v[240:243], v135, s[8:9]
	global_load_dwordx4 v[244:247], v135, s[8:9] offset:64
	global_load_dwordx4 v[156:159], v135, s[8:9] offset:512
	global_load_dwordx4 v[160:163], v135, s[8:9] offset:576
	s_waitcnt vmcnt(8)
	v_pk_fma_f32 v[108:109], v[108:109], v[140:141], v[180:181]
	v_pk_fma_f32 v[110:111], v[110:111], v[142:143], v[182:183]
	v_pk_mul_f32 v[248:249], v[108:109], v[108:109]
	v_pk_fma_f32 v[248:249], v[110:111], v[110:111], v[248:249]
	v_pk_fma_f32 v[76:77], v[76:77], v[144:145], v[184:185]
	v_pk_fma_f32 v[78:79], v[78:79], v[146:147], v[186:187]
	v_pk_fma_f32 v[248:249], v[76:77], v[76:77], v[248:249]
	v_pk_fma_f32 v[248:249], v[78:79], v[78:79], v[248:249]
	v_pk_fma_f32 v[40:41], v[40:41], v[148:149], v[188:189]
	v_pk_fma_f32 v[42:43], v[42:43], v[150:151], v[190:191]
	v_pk_fma_f32 v[248:249], v[40:41], v[40:41], v[248:249]
	v_pk_fma_f32 v[248:249], v[42:43], v[42:43], v[248:249]
	v_pk_fma_f32 v[12:13], v[12:13], v[152:153], v[192:193]
	v_pk_fma_f32 v[14:15], v[14:15], v[154:155], v[194:195]
	v_pk_fma_f32 v[248:249], v[12:13], v[12:13], v[248:249]
	v_pk_fma_f32 v[248:249], v[14:15], v[14:15], v[248:249]
	s_nop 0
	v_add_f32_e32 v204, v248, v249
	v_pk_fma_f32 v[104:105], v[104:105], v[140:141], v[196:197]
	v_pk_fma_f32 v[106:107], v[106:107], v[142:143], v[198:199]
	v_pk_mul_f32 v[248:249], v[104:105], v[104:105]
	v_pk_fma_f32 v[248:249], v[106:107], v[106:107], v[248:249]
	v_pk_fma_f32 v[72:73], v[72:73], v[144:145], v[200:201]
	v_pk_fma_f32 v[74:75], v[74:75], v[146:147], v[202:203]
	v_pk_fma_f32 v[248:249], v[72:73], v[72:73], v[248:249]
	v_pk_fma_f32 v[248:249], v[74:75], v[74:75], v[248:249]
	v_pk_fma_f32 v[32:33], v[32:33], v[148:149], v[212:213]
	v_pk_fma_f32 v[34:35], v[34:35], v[150:151], v[214:215]
	v_pk_fma_f32 v[248:249], v[32:33], v[32:33], v[248:249]
	v_pk_fma_f32 v[248:249], v[34:35], v[34:35], v[248:249]
	v_pk_fma_f32 v[8:9], v[8:9], v[152:153], v[216:217]
	v_pk_fma_f32 v[10:11], v[10:11], v[154:155], v[218:219]
	v_pk_fma_f32 v[248:249], v[8:9], v[8:9], v[248:249]
	v_pk_fma_f32 v[248:249], v[10:11], v[10:11], v[248:249]
	s_nop 0
	v_add_f32_e32 v205, v248, v249
	s_waitcnt vmcnt(0)
	v_pk_fma_f32 v[92:93], v[92:93], v[140:141], v[220:221]
	v_pk_fma_f32 v[94:95], v[94:95], v[142:143], v[222:223]
	v_pk_mul_f32 v[248:249], v[92:93], v[92:93]
	v_pk_fma_f32 v[248:249], v[94:95], v[94:95], v[248:249]
	v_pk_fma_f32 v[60:61], v[60:61], v[144:145], v[224:225]
	v_pk_fma_f32 v[62:63], v[62:63], v[146:147], v[226:227]
	v_pk_fma_f32 v[248:249], v[60:61], v[60:61], v[248:249]
	v_pk_fma_f32 v[248:249], v[62:63], v[62:63], v[248:249]
	v_pk_fma_f32 v[24:25], v[24:25], v[148:149], v[232:233]
	v_pk_fma_f32 v[26:27], v[26:27], v[150:151], v[234:235]
	v_pk_fma_f32 v[248:249], v[24:25], v[24:25], v[248:249]
	v_pk_fma_f32 v[248:249], v[26:27], v[26:27], v[248:249]
	v_pk_fma_f32 v[4:5], v[4:5], v[152:153], v[236:237]
	v_pk_fma_f32 v[6:7], v[6:7], v[154:155], v[238:239]
	v_pk_fma_f32 v[248:249], v[4:5], v[4:5], v[248:249]
	v_pk_fma_f32 v[248:249], v[6:7], v[6:7], v[248:249]
	s_nop 0
	v_add_f32_e32 v228, v248, v249
	v_pk_fma_f32 v[84:85], v[84:85], v[140:141], v[240:241]
	v_pk_fma_f32 v[86:87], v[86:87], v[142:143], v[242:243]
	v_pk_mul_f32 v[248:249], v[84:85], v[84:85]
	v_pk_fma_f32 v[248:249], v[86:87], v[86:87], v[248:249]
	v_pk_fma_f32 v[56:57], v[56:57], v[144:145], v[244:245]
	v_pk_fma_f32 v[58:59], v[58:59], v[146:147], v[246:247]
	v_pk_fma_f32 v[248:249], v[56:57], v[56:57], v[248:249]
	v_pk_fma_f32 v[248:249], v[58:59], v[58:59], v[248:249]
	v_pk_fma_f32 v[16:17], v[16:17], v[148:149], v[156:157]
	v_pk_fma_f32 v[18:19], v[18:19], v[150:151], v[158:159]
	v_pk_fma_f32 v[248:249], v[16:17], v[16:17], v[248:249]
	v_pk_fma_f32 v[248:249], v[18:19], v[18:19], v[248:249]
	v_pk_fma_f32 v[0:1], v[0:1], v[152:153], v[160:161]
	v_pk_fma_f32 v[2:3], v[2:3], v[154:155], v[162:163]
	v_pk_fma_f32 v[248:249], v[0:1], v[0:1], v[248:249]
	v_pk_fma_f32 v[248:249], v[2:3], v[2:3], v[248:249]
	s_nop 0
	v_add_f32_e32 v229, v248, v249
	ds_bpermute_b32 v180, v137, v164
	ds_bpermute_b32 v181, v137, v165
	ds_bpermute_b32 v182, v137, v166
	ds_bpermute_b32 v183, v137, v167
	ds_bpermute_b32 v184, v137, v204
	ds_bpermute_b32 v185, v137, v205
	ds_bpermute_b32 v186, v137, v228
	ds_bpermute_b32 v187, v137, v229
	s_waitcnt lgkmcnt(0)
	v_add_f32_e32 v164, v164, v180
	v_add_f32_e32 v165, v165, v181
	v_add_f32_e32 v166, v166, v182
	v_add_f32_e32 v167, v167, v183
	v_add_f32_e32 v204, v204, v184
	v_add_f32_e32 v205, v205, v185
	v_add_f32_e32 v228, v228, v186
	v_add_f32_e32 v229, v229, v187
	ds_bpermute_b32 v180, v138, v164
	ds_bpermute_b32 v181, v138, v165
	ds_bpermute_b32 v182, v138, v166
	ds_bpermute_b32 v183, v138, v167
	ds_bpermute_b32 v184, v138, v204
	ds_bpermute_b32 v185, v138, v205
	ds_bpermute_b32 v186, v138, v228
	ds_bpermute_b32 v187, v138, v229
	s_waitcnt lgkmcnt(0)
	v_add_f32_e32 v164, v164, v180
	v_add_f32_e32 v165, v165, v181
	v_add_f32_e32 v166, v166, v182
	v_add_f32_e32 v167, v167, v183
	v_add_f32_e32 v204, v204, v184
	v_add_f32_e32 v205, v205, v185
	v_add_f32_e32 v228, v228, v186
	v_add_f32_e32 v229, v229, v187
	v_lshrrev_b32_e32 v140, 5, v208
	v_and_b32_e32 v140, 3, v140
	v_lshlrev_b32_e32 v142, 4, v206
	v_add_u32_e32 v142, 0x20400, v142
	v_lshl_add_u32 v141, v140, 2, v142
	v_lshl_add_u32 v144, s40, 8, v206
	v_lshlrev_b32_e32 v144, 4, v144
	v_mov_b32_e32 v143, s41
	v_lshl_add_u32 v143, v143, 2, v144
	s_mov_b64 exec, 0xffff
	ds_write_b32 v141, v164
	ds_write_b32 v141, v165 offset:256
	ds_write_b32 v141, v166 offset:512
	ds_write_b32 v141, v167 offset:768
	ds_write_b32 v141, v204 offset:2048
	ds_write_b32 v141, v205 offset:2304
	ds_write_b32 v141, v228 offset:2560
	ds_write_b32 v141, v229 offset:2816
	s_mov_b64 exec, -1
	s_waitcnt lgkmcnt(0)
	s_barrier
	ds_read_b128 v[220:223], v142
	ds_read_b128 v[224:227], v142 offset:256
	ds_read_b128 v[232:235], v142 offset:512
	ds_read_b128 v[236:239], v142 offset:768
	ds_read_b128 v[240:243], v142 offset:2048
	ds_read_b128 v[244:247], v142 offset:2304
	ds_read_b128 v[156:159], v142 offset:2560
	ds_read_b128 v[160:163], v142 offset:2816
	s_waitcnt lgkmcnt(0)
	v_add_f32_e32 v248, v220, v221
	v_add_f32_e32 v249, v222, v223
	v_add_f32_e32 v164, v248, v249
	v_add_f32_e32 v248, v224, v225
	v_add_f32_e32 v249, v226, v227
	v_add_f32_e32 v165, v248, v249
	v_add_f32_e32 v248, v232, v233
	v_add_f32_e32 v249, v234, v235
	v_add_f32_e32 v166, v248, v249
	v_add_f32_e32 v248, v236, v237
	v_add_f32_e32 v249, v238, v239
	v_add_f32_e32 v167, v248, v249
	v_add_f32_e32 v248, v240, v241
	v_add_f32_e32 v249, v242, v243
	v_add_f32_e32 v204, v248, v249
	v_add_f32_e32 v248, v244, v245
	v_add_f32_e32 v249, v246, v247
	v_add_f32_e32 v205, v248, v249
	v_add_f32_e32 v248, v156, v157
	v_add_f32_e32 v249, v158, v159
	v_add_f32_e32 v228, v248, v249
	v_add_f32_e32 v248, v160, v161
	v_add_f32_e32 v249, v162, v163
	v_add_f32_e32 v229, v248, v249
	v_readfirstlane_b32 s24, v140
	s_nop 0
	s_cmp_lg_u32 s24, 0
	s_cbranch_scc1 .Lfn_nosw_p11
	s_mov_b64 exec, 0xffff
	global_atomic_swap v143, v164, s[44:45]
	global_atomic_swap v143, v165, s[44:45] offset:256
	global_atomic_swap v143, v166, s[44:45] offset:512
	global_atomic_swap v143, v167, s[44:45] offset:768
	global_atomic_swap v143, v204, s[44:45] offset:2048
	global_atomic_swap v143, v205, s[44:45] offset:2304
	global_atomic_swap v143, v228, s[44:45] offset:2560
	global_atomic_swap v143, v229, s[44:45] offset:2816
	s_mov_b64 exec, -1

.Lfn_meet_p11:
	s_or_b64 exec, exec, s[22:23]
	s_barrier
	global_load_dwordx4 v[220:223], v144, s[44:45] sc1
	global_load_dwordx4 v[224:227], v144, s[44:45] offset:256 sc1
	global_load_dwordx4 v[232:235], v144, s[44:45] offset:512 sc1
	global_load_dwordx4 v[236:239], v144, s[44:45] offset:768 sc1
	global_load_dwordx4 v[240:243], v144, s[44:45] offset:2048 sc1
	global_load_dwordx4 v[244:247], v144, s[44:45] offset:2304 sc1
	global_load_dwordx4 v[156:159], v144, s[44:45] offset:2560 sc1
	global_load_dwordx4 v[160:163], v144, s[44:45] offset:2816 sc1
	s_waitcnt vmcnt(0)
	v_add_f32_e32 v248, v220, v221
	v_add_f32_e32 v249, v222, v223
	v_add_f32_e32 v146, v248, v249
	v_add_f32_e32 v248, v224, v225
	v_add_f32_e32 v249, v226, v227
	v_add_f32_e32 v147, v248, v249
	v_add_f32_e32 v248, v232, v233
	v_add_f32_e32 v249, v234, v235
	v_add_f32_e32 v148, v248, v249
	v_add_f32_e32 v248, v236, v237
	v_add_f32_e32 v249, v238, v239
	v_add_f32_e32 v149, v248, v249
	v_add_f32_e32 v248, v240, v241
	v_add_f32_e32 v249, v242, v243
	v_add_f32_e32 v150, v248, v249
	v_add_f32_e32 v248, v244, v245
	v_add_f32_e32 v249, v246, v247
	v_add_f32_e32 v151, v248, v249
	v_add_f32_e32 v248, v156, v157
	v_add_f32_e32 v249, v158, v159
	v_add_f32_e32 v152, v248, v249
	v_add_f32_e32 v248, v160, v161
	v_add_f32_e32 v249, v162, v163
	v_add_f32_e32 v153, v248, v249
	global_load_dwordx4 v[180:183], v136, s[42:43]
	global_load_dwordx4 v[184:187], v136, s[42:43] offset:64
	global_load_dwordx4 v[188:191], v136, s[42:43] offset:512
	global_load_dwordx4 v[192:195], v136, s[42:43] offset:576
	global_load_dwordx4 v[220:223], v136, s[70:71]
	global_load_dwordx4 v[224:227], v136, s[70:71] offset:64
	global_load_dwordx4 v[232:235], v136, s[70:71] offset:512
	global_load_dwordx4 v[236:239], v136, s[70:71] offset:576
	global_load_dwordx4 v[240:243], v136, s[72:73]
	global_load_dwordx4 v[244:247], v136, s[72:73] offset:64
	global_load_dwordx4 v[156:159], v136, s[72:73] offset:512
	global_load_dwordx4 v[160:163], v136, s[72:73] offset:576
	v_mov_b32_e32 v228, 0x358637bd
	v_mov_b32_e32 v229, 0x260
	s_mov_b32 s14, 0xf800000
	v_fmamk_f32 v146, v146, 0x3a800000, v228
	v_mul_f32_e32 v164, 0x4f800000, v146
	v_cmp_gt_f32_e32 vcc, s14, v146
	s_nop 1
	v_cndmask_b32_e32 v146, v146, v164, vcc
	v_sqrt_f32_e32 v165, v146
	s_nop 1
	v_add_u32_e32 v166, -1, v165
	v_add_u32_e32 v167, 1, v165
	v_fma_f32 v204, -v166, v165, v146
	v_fma_f32 v205, -v167, v165, v146
	v_cmp_ge_f32_e64 s[26:27], 0, v204
	s_nop 1
	v_cndmask_b32_e64 v165, v165, v166, s[26:27]
	v_cmp_lt_f32_e64 s[26:27], 0, v205
	s_nop 1
	v_cndmask_b32_e64 v165, v165, v167, s[26:27]
	v_mul_f32_e32 v166, 0x37800000, v165
	v_cndmask_b32_e32 v165, v165, v166, vcc
	v_cmp_class_f32_e32 vcc, v146, v229
	s_nop 1
	v_cndmask_b32_e32 v146, v165, v146, vcc
	v_div_scale_f32 v164, s[26:27], v146, v146, 1.0
	v_rcp_f32_e32 v165, v164
	v_div_scale_f32 v166, vcc, 1.0, v146, 1.0
	v_fma_f32 v167, -v164, v165, 1.0
	v_fmac_f32_e32 v165, v167, v165
	v_mul_f32_e32 v167, v166, v165
	v_fma_f32 v204, -v164, v167, v166
	v_fmac_f32_e32 v167, v204, v165
	v_fma_f32 v164, -v164, v167, v166
	v_div_fmas_f32 v167, v164, v165, v167
	v_div_fixup_f32 v196, v167, v146, 1.0
	v_fmamk_f32 v147, v147, 0x3a800000, v228
	v_mul_f32_e32 v164, 0x4f800000, v147
	v_cmp_gt_f32_e32 vcc, s14, v147
	s_nop 1
	v_cndmask_b32_e32 v147, v147, v164, vcc
	v_sqrt_f32_e32 v165, v147
	s_nop 1
	v_add_u32_e32 v166, -1, v165
	v_add_u32_e32 v167, 1, v165
	v_fma_f32 v204, -v166, v165, v147
	v_fma_f32 v205, -v167, v165, v147
	v_cmp_ge_f32_e64 s[26:27], 0, v204
	s_nop 1
	v_cndmask_b32_e64 v165, v165, v166, s[26:27]
	v_cmp_lt_f32_e64 s[26:27], 0, v205
	s_nop 1
	v_cndmask_b32_e64 v165, v165, v167, s[26:27]
	v_mul_f32_e32 v166, 0x37800000, v165
	v_cndmask_b32_e32 v165, v165, v166, vcc
	v_cmp_class_f32_e32 vcc, v147, v229
	s_nop 1
	v_cndmask_b32_e32 v147, v165, v147, vcc
	v_div_scale_f32 v164, s[26:27], v147, v147, 1.0
	v_rcp_f32_e32 v165, v164
	v_div_scale_f32 v166, vcc, 1.0, v147, 1.0
	v_fma_f32 v167, -v164, v165, 1.0
	v_fmac_f32_e32 v165, v167, v165
	v_mul_f32_e32 v167, v166, v165
	v_fma_f32 v204, -v164, v167, v166
	v_fmac_f32_e32 v167, v204, v165
	v_fma_f32 v164, -v164, v167, v166
	v_div_fmas_f32 v167, v164, v165, v167
	v_div_fixup_f32 v198, v167, v147, 1.0
	v_fmamk_f32 v148, v148, 0x3a800000, v228
	v_mul_f32_e32 v164, 0x4f800000, v148
	v_cmp_gt_f32_e32 vcc, s14, v148
	s_nop 1
	v_cndmask_b32_e32 v148, v148, v164, vcc
	v_sqrt_f32_e32 v165, v148
	s_nop 1
	v_add_u32_e32 v166, -1, v165
	v_add_u32_e32 v167, 1, v165
	v_fma_f32 v204, -v166, v165, v148
	v_fma_f32 v205, -v167, v165, v148
	v_cmp_ge_f32_e64 s[26:27], 0, v204
	s_nop 1
	v_cndmask_b32_e64 v165, v165, v166, s[26:27]
	v_cmp_lt_f32_e64 s[26:27], 0, v205
	s_nop 1
	v_cndmask_b32_e64 v165, v165, v167, s[26:27]
	v_mul_f32_e32 v166, 0x37800000, v165
	v_cndmask_b32_e32 v165, v165, v166, vcc
	v_cmp_class_f32_e32 vcc, v148, v229
	s_nop 1
	v_cndmask_b32_e32 v148, v165, v148, vcc
	v_div_scale_f32 v164, s[26:27], v148, v148, 1.0
	v_rcp_f32_e32 v165, v164
	v_div_scale_f32 v166, vcc, 1.0, v148, 1.0
	v_fma_f32 v167, -v164, v165, 1.0
	v_fmac_f32_e32 v165, v167, v165
	v_mul_f32_e32 v167, v166, v165
	v_fma_f32 v204, -v164, v167, v166
	v_fmac_f32_e32 v167, v204, v165
	v_fma_f32 v164, -v164, v167, v166
	v_div_fmas_f32 v167, v164, v165, v167
	v_div_fixup_f32 v200, v167, v148, 1.0
	v_fmamk_f32 v149, v149, 0x3a800000, v228
	v_mul_f32_e32 v164, 0x4f800000, v149
	v_cmp_gt_f32_e32 vcc, s14, v149
	s_nop 1
	v_cndmask_b32_e32 v149, v149, v164, vcc
	v_sqrt_f32_e32 v165, v149
	s_nop 1
	v_add_u32_e32 v166, -1, v165
	v_add_u32_e32 v167, 1, v165
	v_fma_f32 v204, -v166, v165, v149
	v_fma_f32 v205, -v167, v165, v149
	v_cmp_ge_f32_e64 s[26:27], 0, v204
	s_nop 1
	v_cndmask_b32_e64 v165, v165, v166, s[26:27]
	v_cmp_lt_f32_e64 s[26:27], 0, v205
	s_nop 1
	v_cndmask_b32_e64 v165, v165, v167, s[26:27]
	v_mul_f32_e32 v166, 0x37800000, v165
	v_cndmask_b32_e32 v165, v165, v166, vcc
	v_cmp_class_f32_e32 vcc, v149, v229
	s_nop 1
	v_cndmask_b32_e32 v149, v165, v149, vcc
	v_div_scale_f32 v164, s[26:27], v149, v149, 1.0
	v_rcp_f32_e32 v165, v164
	v_div_scale_f32 v166, vcc, 1.0, v149, 1.0
	v_fma_f32 v167, -v164, v165, 1.0
	v_fmac_f32_e32 v165, v167, v165
	v_mul_f32_e32 v167, v166, v165
	v_fma_f32 v204, -v164, v167, v166
	v_fmac_f32_e32 v167, v204, v165
	v_fma_f32 v164, -v164, v167, v166
	v_div_fmas_f32 v167, v164, v165, v167
	v_div_fixup_f32 v202, v167, v149, 1.0
	v_fmamk_f32 v150, v150, 0x3a800000, v228
	v_mul_f32_e32 v164, 0x4f800000, v150
	v_cmp_gt_f32_e32 vcc, s14, v150
	s_nop 1
	v_cndmask_b32_e32 v150, v150, v164, vcc
	v_sqrt_f32_e32 v165, v150
	s_nop 1
	v_add_u32_e32 v166, -1, v165
	v_add_u32_e32 v167, 1, v165
	v_fma_f32 v204, -v166, v165, v150
	v_fma_f32 v205, -v167, v165, v150
	v_cmp_ge_f32_e64 s[26:27], 0, v204
	s_nop 1
	v_cndmask_b32_e64 v165, v165, v166, s[26:27]
	v_cmp_lt_f32_e64 s[26:27], 0, v205
	s_nop 1
	v_cndmask_b32_e64 v165, v165, v167, s[26:27]
	v_mul_f32_e32 v166, 0x37800000, v165
	v_cndmask_b32_e32 v165, v165, v166, vcc
	v_cmp_class_f32_e32 vcc, v150, v229
	s_nop 1
	v_cndmask_b32_e32 v150, v165, v150, vcc
	v_div_scale_f32 v164, s[26:27], v150, v150, 1.0
	v_rcp_f32_e32 v165, v164
	v_div_scale_f32 v166, vcc, 1.0, v150, 1.0
	v_fma_f32 v167, -v164, v165, 1.0
	v_fmac_f32_e32 v165, v167, v165
	v_mul_f32_e32 v167, v166, v165
	v_fma_f32 v204, -v164, v167, v166
	v_fmac_f32_e32 v167, v204, v165
	v_fma_f32 v164, -v164, v167, v166
	v_div_fmas_f32 v167, v164, v165, v167
	v_div_fixup_f32 v212, v167, v150, 1.0
	v_fmamk_f32 v151, v151, 0x3a800000, v228
	v_mul_f32_e32 v164, 0x4f800000, v151
	v_cmp_gt_f32_e32 vcc, s14, v151
	s_nop 1
	v_cndmask_b32_e32 v151, v151, v164, vcc
	v_sqrt_f32_e32 v165, v151
	s_nop 1
	v_add_u32_e32 v166, -1, v165
	v_add_u32_e32 v167, 1, v165
	v_fma_f32 v204, -v166, v165, v151
	v_fma_f32 v205, -v167, v165, v151
	v_cmp_ge_f32_e64 s[26:27], 0, v204
	s_nop 1
	v_cndmask_b32_e64 v165, v165, v166, s[26:27]
	v_cmp_lt_f32_e64 s[26:27], 0, v205
	s_nop 1
	v_cndmask_b32_e64 v165, v165, v167, s[26:27]
	v_mul_f32_e32 v166, 0x37800000, v165
	v_cndmask_b32_e32 v165, v165, v166, vcc
	v_cmp_class_f32_e32 vcc, v151, v229
	s_nop 1
	v_cndmask_b32_e32 v151, v165, v151, vcc
	v_div_scale_f32 v164, s[26:27], v151, v151, 1.0
	v_rcp_f32_e32 v165, v164
	v_div_scale_f32 v166, vcc, 1.0, v151, 1.0
	v_fma_f32 v167, -v164, v165, 1.0
	v_fmac_f32_e32 v165, v167, v165
	v_mul_f32_e32 v167, v166, v165
	v_fma_f32 v204, -v164, v167, v166
	v_fmac_f32_e32 v167, v204, v165
	v_fma_f32 v164, -v164, v167, v166
	v_div_fmas_f32 v167, v164, v165, v167
	v_div_fixup_f32 v214, v167, v151, 1.0
	v_fmamk_f32 v152, v152, 0x3a800000, v228
	v_mul_f32_e32 v164, 0x4f800000, v152
	v_cmp_gt_f32_e32 vcc, s14, v152
	s_nop 1
	v_cndmask_b32_e32 v152, v152, v164, vcc
	v_sqrt_f32_e32 v165, v152
	s_nop 1
	v_add_u32_e32 v166, -1, v165
	v_add_u32_e32 v167, 1, v165
	v_fma_f32 v204, -v166, v165, v152
	v_fma_f32 v205, -v167, v165, v152
	v_cmp_ge_f32_e64 s[26:27], 0, v204
	s_nop 1
	v_cndmask_b32_e64 v165, v165, v166, s[26:27]
	v_cmp_lt_f32_e64 s[26:27], 0, v205
	s_nop 1
	v_cndmask_b32_e64 v165, v165, v167, s[26:27]
	v_mul_f32_e32 v166, 0x37800000, v165
	v_cndmask_b32_e32 v165, v165, v166, vcc
	v_cmp_class_f32_e32 vcc, v152, v229
	s_nop 1
	v_cndmask_b32_e32 v152, v165, v152, vcc
	v_div_scale_f32 v164, s[26:27], v152, v152, 1.0
	v_rcp_f32_e32 v165, v164
	v_div_scale_f32 v166, vcc, 1.0, v152, 1.0
	v_fma_f32 v167, -v164, v165, 1.0
	v_fmac_f32_e32 v165, v167, v165
	v_mul_f32_e32 v167, v166, v165
	v_fma_f32 v204, -v164, v167, v166
	v_fmac_f32_e32 v167, v204, v165
	v_fma_f32 v164, -v164, v167, v166
	v_div_fmas_f32 v167, v164, v165, v167
	v_div_fixup_f32 v216, v167, v152, 1.0
	v_fmamk_f32 v153, v153, 0x3a800000, v228
	v_mul_f32_e32 v164, 0x4f800000, v153
	v_cmp_gt_f32_e32 vcc, s14, v153
	s_nop 1
	v_cndmask_b32_e32 v153, v153, v164, vcc
	v_sqrt_f32_e32 v165, v153
	s_nop 1
	v_add_u32_e32 v166, -1, v165
	v_add_u32_e32 v167, 1, v165
	v_fma_f32 v204, -v166, v165, v153
	v_fma_f32 v205, -v167, v165, v153
	v_cmp_ge_f32_e64 s[26:27], 0, v204
	s_nop 1
	v_cndmask_b32_e64 v165, v165, v166, s[26:27]
	v_cmp_lt_f32_e64 s[26:27], 0, v205
	s_nop 1
	v_cndmask_b32_e64 v165, v165, v167, s[26:27]
	v_mul_f32_e32 v166, 0x37800000, v165
	v_cndmask_b32_e32 v165, v165, v166, vcc
	v_cmp_class_f32_e32 vcc, v153, v229
	s_nop 1
	v_cndmask_b32_e32 v153, v165, v153, vcc
	v_div_scale_f32 v164, s[26:27], v153, v153, 1.0
	v_rcp_f32_e32 v165, v164
	v_div_scale_f32 v166, vcc, 1.0, v153, 1.0
	v_fma_f32 v167, -v164, v165, 1.0
	v_fmac_f32_e32 v165, v167, v165
	v_mul_f32_e32 v167, v166, v165
	v_fma_f32 v204, -v164, v167, v166
	v_fmac_f32_e32 v167, v204, v165
	v_fma_f32 v164, -v164, v167, v166
	v_div_fmas_f32 v167, v164, v165, v167
	v_div_fixup_f32 v218, v167, v153, 1.0
	s_waitcnt vmcnt(0)
	v_pk_add_f32 v[220:221], v[220:221], 1.0 op_sel_hi:[1,0]
	v_pk_add_f32 v[222:223], v[222:223], 1.0 op_sel_hi:[1,0]
	v_pk_add_f32 v[224:225], v[224:225], 1.0 op_sel_hi:[1,0]
	v_pk_add_f32 v[226:227], v[226:227], 1.0 op_sel_hi:[1,0]
	v_pk_add_f32 v[232:233], v[232:233], 1.0 op_sel_hi:[1,0]
	v_pk_add_f32 v[234:235], v[234:235], 1.0 op_sel_hi:[1,0]
	v_pk_add_f32 v[236:237], v[236:237], 1.0 op_sel_hi:[1,0]
	v_pk_add_f32 v[238:239], v[238:239], 1.0 op_sel_hi:[1,0]
	v_and_b32_e32 v144, 16, v230
	v_cmp_ne_u32_e64 s[74:75], 0, v144
	v_mov_b32_e32 v145, 24
	s_nop 0
	v_cndmask_b32_e64 v144, 0, v145, s[74:75]
	global_store_dwordx4 v128, v[124:127], s[8:9]
	global_store_dwordx4 v128, v[100:103], s[8:9] offset:64
	global_store_dwordx4 v128, v[68:71], s[8:9] offset:512
	global_store_dwordx4 v128, v[44:47], s[8:9] offset:576
	v_lshrrev_b32_e32 v139, 1, v128
	v_add_u32_e32 v139, v139, v144
	v_pk_mul_f32 v[124:125], v[124:125], v[196:197] op_sel_hi:[1,0]
	v_pk_mul_f32 v[126:127], v[126:127], v[196:197] op_sel_hi:[1,0]
	v_pk_mul_f32 v[124:125], v[180:181], v[124:125]
	v_pk_mul_f32 v[126:127], v[182:183], v[126:127]
	v_pk_fma_f32 v[124:125], v[220:221], v[124:125], v[240:241]
	v_pk_fma_f32 v[126:127], v[222:223], v[126:127], v[242:243]
	v_cvt_pk_bf16_f32 v124, v124, v125
	v_cvt_pk_bf16_f32 v125, v126, v127
	v_pk_mul_f32 v[100:101], v[100:101], v[196:197] op_sel_hi:[1,0]
	v_pk_mul_f32 v[102:103], v[102:103], v[196:197] op_sel_hi:[1,0]
	v_pk_mul_f32 v[100:101], v[184:185], v[100:101]
	v_pk_mul_f32 v[102:103], v[186:187], v[102:103]
	v_pk_fma_f32 v[100:101], v[224:225], v[100:101], v[244:245]
	v_pk_fma_f32 v[102:103], v[226:227], v[102:103], v[246:247]
	v_cvt_pk_bf16_f32 v100, v100, v101
	v_cvt_pk_bf16_f32 v101, v102, v103
	v_pk_mul_f32 v[68:69], v[68:69], v[196:197] op_sel_hi:[1,0]
	v_pk_mul_f32 v[70:71], v[70:71], v[196:197] op_sel_hi:[1,0]
	v_pk_mul_f32 v[68:69], v[188:189], v[68:69]
	v_pk_mul_f32 v[70:71], v[190:191], v[70:71]
	v_pk_fma_f32 v[68:69], v[232:233], v[68:69], v[156:157]
	v_pk_fma_f32 v[70:71], v[234:235], v[70:71], v[158:159]
	v_cvt_pk_bf16_f32 v68, v68, v69
	v_cvt_pk_bf16_f32 v69, v70, v71
	v_pk_mul_f32 v[44:45], v[44:45], v[196:197] op_sel_hi:[1,0]
	v_pk_mul_f32 v[46:47], v[46:47], v[196:197] op_sel_hi:[1,0]
	v_pk_mul_f32 v[44:45], v[192:193], v[44:45]
	v_pk_mul_f32 v[46:47], v[194:195], v[46:47]
	v_pk_fma_f32 v[44:45], v[236:237], v[44:45], v[160:161]
	v_pk_fma_f32 v[46:47], v[238:239], v[46:47], v[162:163]
	v_cvt_pk_bf16_f32 v44, v44, v45
	v_cvt_pk_bf16_f32 v45, v46, v47
	v_cndmask_b32_e64 v146, v100, v124, s[74:75]
	v_cndmask_b32_e64 v147, v101, v125, s[74:75]
	ds_bpermute_b32 v148, v137, v146
	ds_bpermute_b32 v149, v137, v147
	v_cndmask_b32_e64 v150, v44, v68, s[74:75]
	v_cndmask_b32_e64 v151, v45, v69, s[74:75]
	ds_bpermute_b32 v152, v137, v150
	ds_bpermute_b32 v153, v137, v151
	s_waitcnt lgkmcnt(0)
	v_cndmask_b32_e64 v126, v148, v100, s[74:75]
	v_cndmask_b32_e64 v127, v149, v101, s[74:75]
	v_cndmask_b32_e64 v124, v124, v148, s[74:75]
	v_cndmask_b32_e64 v125, v125, v149, s[74:75]
	global_store_dwordx4 v139, v[124:127], s[68:69]
	v_cndmask_b32_e64 v70, v152, v44, s[74:75]
	v_cndmask_b32_e64 v71, v153, v45, s[74:75]
	v_cndmask_b32_e64 v68, v68, v152, s[74:75]
	v_cndmask_b32_e64 v69, v69, v153, s[74:75]
	global_store_dwordx4 v139, v[68:71], s[68:69] offset:256
	global_store_dwordx4 v129, v[120:123], s[8:9]
	global_store_dwordx4 v129, v[96:99], s[8:9] offset:64
	global_store_dwordx4 v129, v[64:67], s[8:9] offset:512
	global_store_dwordx4 v129, v[36:39], s[8:9] offset:576
	v_lshrrev_b32_e32 v139, 1, v129
	v_add_u32_e32 v139, v139, v144
	v_pk_mul_f32 v[120:121], v[120:121], v[198:199] op_sel_hi:[1,0]
	v_pk_mul_f32 v[122:123], v[122:123], v[198:199] op_sel_hi:[1,0]
	v_pk_mul_f32 v[120:121], v[180:181], v[120:121]
	v_pk_mul_f32 v[122:123], v[182:183], v[122:123]
	v_pk_fma_f32 v[120:121], v[220:221], v[120:121], v[240:241]
	v_pk_fma_f32 v[122:123], v[222:223], v[122:123], v[242:243]
	v_cvt_pk_bf16_f32 v120, v120, v121
	v_cvt_pk_bf16_f32 v121, v122, v123
	v_pk_mul_f32 v[96:97], v[96:97], v[198:199] op_sel_hi:[1,0]
	v_pk_mul_f32 v[98:99], v[98:99], v[198:199] op_sel_hi:[1,0]
	v_pk_mul_f32 v[96:97], v[184:185], v[96:97]
	v_pk_mul_f32 v[98:99], v[186:187], v[98:99]
	v_pk_fma_f32 v[96:97], v[224:225], v[96:97], v[244:245]
	v_pk_fma_f32 v[98:99], v[226:227], v[98:99], v[246:247]
	v_cvt_pk_bf16_f32 v96, v96, v97
	v_cvt_pk_bf16_f32 v97, v98, v99
	v_pk_mul_f32 v[64:65], v[64:65], v[198:199] op_sel_hi:[1,0]
	v_pk_mul_f32 v[66:67], v[66:67], v[198:199] op_sel_hi:[1,0]
	v_pk_mul_f32 v[64:65], v[188:189], v[64:65]
	v_pk_mul_f32 v[66:67], v[190:191], v[66:67]
	v_pk_fma_f32 v[64:65], v[232:233], v[64:65], v[156:157]
	v_pk_fma_f32 v[66:67], v[234:235], v[66:67], v[158:159]
	v_cvt_pk_bf16_f32 v64, v64, v65
	v_cvt_pk_bf16_f32 v65, v66, v67
	v_pk_mul_f32 v[36:37], v[36:37], v[198:199] op_sel_hi:[1,0]
	v_pk_mul_f32 v[38:39], v[38:39], v[198:199] op_sel_hi:[1,0]
	v_pk_mul_f32 v[36:37], v[192:193], v[36:37]
	v_pk_mul_f32 v[38:39], v[194:195], v[38:39]
	v_pk_fma_f32 v[36:37], v[236:237], v[36:37], v[160:161]
	v_pk_fma_f32 v[38:39], v[238:239], v[38:39], v[162:163]
	v_cvt_pk_bf16_f32 v36, v36, v37
	v_cvt_pk_bf16_f32 v37, v38, v39
	v_cndmask_b32_e64 v146, v96, v120, s[74:75]
	v_cndmask_b32_e64 v147, v97, v121, s[74:75]
	ds_bpermute_b32 v148, v137, v146
	ds_bpermute_b32 v149, v137, v147
	v_cndmask_b32_e64 v150, v36, v64, s[74:75]
	v_cndmask_b32_e64 v151, v37, v65, s[74:75]
	ds_bpermute_b32 v152, v137, v150
	ds_bpermute_b32 v153, v137, v151
	s_waitcnt lgkmcnt(0)
	v_cndmask_b32_e64 v122, v148, v96, s[74:75]
	v_cndmask_b32_e64 v123, v149, v97, s[74:75]
	v_cndmask_b32_e64 v120, v120, v148, s[74:75]
	v_cndmask_b32_e64 v121, v121, v149, s[74:75]
	global_store_dwordx4 v139, v[120:123], s[68:69]
	v_cndmask_b32_e64 v66, v152, v36, s[74:75]
	v_cndmask_b32_e64 v67, v153, v37, s[74:75]
	v_cndmask_b32_e64 v64, v64, v152, s[74:75]
	v_cndmask_b32_e64 v65, v65, v153, s[74:75]
	global_store_dwordx4 v139, v[64:67], s[68:69] offset:256
	global_store_dwordx4 v130, v[116:119], s[8:9]
	global_store_dwordx4 v130, v[88:91], s[8:9] offset:64
	global_store_dwordx4 v130, v[52:55], s[8:9] offset:512
	global_store_dwordx4 v130, v[28:31], s[8:9] offset:576
	v_lshrrev_b32_e32 v139, 1, v130
	v_add_u32_e32 v139, v139, v144
	v_pk_mul_f32 v[116:117], v[116:117], v[200:201] op_sel_hi:[1,0]
	v_pk_mul_f32 v[118:119], v[118:119], v[200:201] op_sel_hi:[1,0]
	v_pk_mul_f32 v[116:117], v[180:181], v[116:117]
	v_pk_mul_f32 v[118:119], v[182:183], v[118:119]
	v_pk_fma_f32 v[116:117], v[220:221], v[116:117], v[240:241]
	v_pk_fma_f32 v[118:119], v[222:223], v[118:119], v[242:243]
	v_cvt_pk_bf16_f32 v116, v116, v117
	v_cvt_pk_bf16_f32 v117, v118, v119
	v_pk_mul_f32 v[88:89], v[88:89], v[200:201] op_sel_hi:[1,0]
	v_pk_mul_f32 v[90:91], v[90:91], v[200:201] op_sel_hi:[1,0]
	v_pk_mul_f32 v[88:89], v[184:185], v[88:89]
	v_pk_mul_f32 v[90:91], v[186:187], v[90:91]
	v_pk_fma_f32 v[88:89], v[224:225], v[88:89], v[244:245]
	v_pk_fma_f32 v[90:91], v[226:227], v[90:91], v[246:247]
	v_cvt_pk_bf16_f32 v88, v88, v89
	v_cvt_pk_bf16_f32 v89, v90, v91
	v_pk_mul_f32 v[52:53], v[52:53], v[200:201] op_sel_hi:[1,0]
	v_pk_mul_f32 v[54:55], v[54:55], v[200:201] op_sel_hi:[1,0]
	v_pk_mul_f32 v[52:53], v[188:189], v[52:53]
	v_pk_mul_f32 v[54:55], v[190:191], v[54:55]
	v_pk_fma_f32 v[52:53], v[232:233], v[52:53], v[156:157]
	v_pk_fma_f32 v[54:55], v[234:235], v[54:55], v[158:159]
	v_cvt_pk_bf16_f32 v52, v52, v53
	v_cvt_pk_bf16_f32 v53, v54, v55
	v_pk_mul_f32 v[28:29], v[28:29], v[200:201] op_sel_hi:[1,0]
	v_pk_mul_f32 v[30:31], v[30:31], v[200:201] op_sel_hi:[1,0]
	v_pk_mul_f32 v[28:29], v[192:193], v[28:29]
	v_pk_mul_f32 v[30:31], v[194:195], v[30:31]
	v_pk_fma_f32 v[28:29], v[236:237], v[28:29], v[160:161]
	v_pk_fma_f32 v[30:31], v[238:239], v[30:31], v[162:163]
	v_cvt_pk_bf16_f32 v28, v28, v29
	v_cvt_pk_bf16_f32 v29, v30, v31
	v_cndmask_b32_e64 v146, v88, v116, s[74:75]
	v_cndmask_b32_e64 v147, v89, v117, s[74:75]
	ds_bpermute_b32 v148, v137, v146
	ds_bpermute_b32 v149, v137, v147
	v_cndmask_b32_e64 v150, v28, v52, s[74:75]
	v_cndmask_b32_e64 v151, v29, v53, s[74:75]
	ds_bpermute_b32 v152, v137, v150
	ds_bpermute_b32 v153, v137, v151
	s_waitcnt lgkmcnt(0)
	v_cndmask_b32_e64 v118, v148, v88, s[74:75]
	v_cndmask_b32_e64 v119, v149, v89, s[74:75]
	v_cndmask_b32_e64 v116, v116, v148, s[74:75]
	v_cndmask_b32_e64 v117, v117, v149, s[74:75]
	global_store_dwordx4 v139, v[116:119], s[68:69]
	v_cndmask_b32_e64 v54, v152, v28, s[74:75]
	v_cndmask_b32_e64 v55, v153, v29, s[74:75]
	v_cndmask_b32_e64 v52, v52, v152, s[74:75]
	v_cndmask_b32_e64 v53, v53, v153, s[74:75]
	global_store_dwordx4 v139, v[52:55], s[68:69] offset:256
	global_store_dwordx4 v131, v[112:115], s[8:9]
	global_store_dwordx4 v131, v[80:83], s[8:9] offset:64
	global_store_dwordx4 v131, v[48:51], s[8:9] offset:512
	global_store_dwordx4 v131, v[20:23], s[8:9] offset:576
	v_lshrrev_b32_e32 v139, 1, v131
	v_add_u32_e32 v139, v139, v144
	v_pk_mul_f32 v[112:113], v[112:113], v[202:203] op_sel_hi:[1,0]
	v_pk_mul_f32 v[114:115], v[114:115], v[202:203] op_sel_hi:[1,0]
	v_pk_mul_f32 v[112:113], v[180:181], v[112:113]
	v_pk_mul_f32 v[114:115], v[182:183], v[114:115]
	v_pk_fma_f32 v[112:113], v[220:221], v[112:113], v[240:241]
	v_pk_fma_f32 v[114:115], v[222:223], v[114:115], v[242:243]
	v_cvt_pk_bf16_f32 v112, v112, v113
	v_cvt_pk_bf16_f32 v113, v114, v115
	v_pk_mul_f32 v[80:81], v[80:81], v[202:203] op_sel_hi:[1,0]
	v_pk_mul_f32 v[82:83], v[82:83], v[202:203] op_sel_hi:[1,0]
	v_pk_mul_f32 v[80:81], v[184:185], v[80:81]
	v_pk_mul_f32 v[82:83], v[186:187], v[82:83]
	v_pk_fma_f32 v[80:81], v[224:225], v[80:81], v[244:245]
	v_pk_fma_f32 v[82:83], v[226:227], v[82:83], v[246:247]
	v_cvt_pk_bf16_f32 v80, v80, v81
	v_cvt_pk_bf16_f32 v81, v82, v83
	v_pk_mul_f32 v[48:49], v[48:49], v[202:203] op_sel_hi:[1,0]
	v_pk_mul_f32 v[50:51], v[50:51], v[202:203] op_sel_hi:[1,0]
	v_pk_mul_f32 v[48:49], v[188:189], v[48:49]
	v_pk_mul_f32 v[50:51], v[190:191], v[50:51]
	v_pk_fma_f32 v[48:49], v[232:233], v[48:49], v[156:157]
	v_pk_fma_f32 v[50:51], v[234:235], v[50:51], v[158:159]
	v_cvt_pk_bf16_f32 v48, v48, v49
	v_cvt_pk_bf16_f32 v49, v50, v51
	v_pk_mul_f32 v[20:21], v[20:21], v[202:203] op_sel_hi:[1,0]
	v_pk_mul_f32 v[22:23], v[22:23], v[202:203] op_sel_hi:[1,0]
	v_pk_mul_f32 v[20:21], v[192:193], v[20:21]
	v_pk_mul_f32 v[22:23], v[194:195], v[22:23]
	v_pk_fma_f32 v[20:21], v[236:237], v[20:21], v[160:161]
	v_pk_fma_f32 v[22:23], v[238:239], v[22:23], v[162:163]
	v_cvt_pk_bf16_f32 v20, v20, v21
	v_cvt_pk_bf16_f32 v21, v22, v23
	v_cndmask_b32_e64 v146, v80, v112, s[74:75]
	v_cndmask_b32_e64 v147, v81, v113, s[74:75]
	ds_bpermute_b32 v148, v137, v146
	ds_bpermute_b32 v149, v137, v147
	v_cndmask_b32_e64 v150, v20, v48, s[74:75]
	v_cndmask_b32_e64 v151, v21, v49, s[74:75]
	ds_bpermute_b32 v152, v137, v150
	ds_bpermute_b32 v153, v137, v151
	s_waitcnt lgkmcnt(0)
	v_cndmask_b32_e64 v114, v148, v80, s[74:75]
	v_cndmask_b32_e64 v115, v149, v81, s[74:75]
	v_cndmask_b32_e64 v112, v112, v148, s[74:75]
	v_cndmask_b32_e64 v113, v113, v149, s[74:75]
	global_store_dwordx4 v139, v[112:115], s[68:69]
	v_cndmask_b32_e64 v50, v152, v20, s[74:75]
	v_cndmask_b32_e64 v51, v153, v21, s[74:75]
	v_cndmask_b32_e64 v48, v48, v152, s[74:75]
	v_cndmask_b32_e64 v49, v49, v153, s[74:75]
	global_store_dwordx4 v139, v[48:51], s[68:69] offset:256
	global_store_dwordx4 v132, v[108:111], s[8:9]
	global_store_dwordx4 v132, v[76:79], s[8:9] offset:64
	global_store_dwordx4 v132, v[40:43], s[8:9] offset:512
	global_store_dwordx4 v132, v[12:15], s[8:9] offset:576
	v_lshrrev_b32_e32 v139, 1, v132
	v_add_u32_e32 v139, v139, v144
	v_pk_mul_f32 v[108:109], v[108:109], v[212:213] op_sel_hi:[1,0]
	v_pk_mul_f32 v[110:111], v[110:111], v[212:213] op_sel_hi:[1,0]
	v_pk_mul_f32 v[108:109], v[180:181], v[108:109]
	v_pk_mul_f32 v[110:111], v[182:183], v[110:111]
	v_pk_fma_f32 v[108:109], v[220:221], v[108:109], v[240:241]
	v_pk_fma_f32 v[110:111], v[222:223], v[110:111], v[242:243]
	v_cvt_pk_bf16_f32 v108, v108, v109
	v_cvt_pk_bf16_f32 v109, v110, v111
	v_pk_mul_f32 v[76:77], v[76:77], v[212:213] op_sel_hi:[1,0]
	v_pk_mul_f32 v[78:79], v[78:79], v[212:213] op_sel_hi:[1,0]
	v_pk_mul_f32 v[76:77], v[184:185], v[76:77]
	v_pk_mul_f32 v[78:79], v[186:187], v[78:79]
	v_pk_fma_f32 v[76:77], v[224:225], v[76:77], v[244:245]
	v_pk_fma_f32 v[78:79], v[226:227], v[78:79], v[246:247]
	v_cvt_pk_bf16_f32 v76, v76, v77
	v_cvt_pk_bf16_f32 v77, v78, v79
	v_pk_mul_f32 v[40:41], v[40:41], v[212:213] op_sel_hi:[1,0]
	v_pk_mul_f32 v[42:43], v[42:43], v[212:213] op_sel_hi:[1,0]
	v_pk_mul_f32 v[40:41], v[188:189], v[40:41]
	v_pk_mul_f32 v[42:43], v[190:191], v[42:43]
	v_pk_fma_f32 v[40:41], v[232:233], v[40:41], v[156:157]
	v_pk_fma_f32 v[42:43], v[234:235], v[42:43], v[158:159]
	v_cvt_pk_bf16_f32 v40, v40, v41
	v_cvt_pk_bf16_f32 v41, v42, v43
	v_pk_mul_f32 v[12:13], v[12:13], v[212:213] op_sel_hi:[1,0]
	v_pk_mul_f32 v[14:15], v[14:15], v[212:213] op_sel_hi:[1,0]
	v_pk_mul_f32 v[12:13], v[192:193], v[12:13]
	v_pk_mul_f32 v[14:15], v[194:195], v[14:15]
	v_pk_fma_f32 v[12:13], v[236:237], v[12:13], v[160:161]
	v_pk_fma_f32 v[14:15], v[238:239], v[14:15], v[162:163]
	v_cvt_pk_bf16_f32 v12, v12, v13
	v_cvt_pk_bf16_f32 v13, v14, v15
	v_cndmask_b32_e64 v146, v76, v108, s[74:75]
	v_cndmask_b32_e64 v147, v77, v109, s[74:75]
	ds_bpermute_b32 v148, v137, v146
	ds_bpermute_b32 v149, v137, v147
	v_cndmask_b32_e64 v150, v12, v40, s[74:75]
	v_cndmask_b32_e64 v151, v13, v41, s[74:75]
	ds_bpermute_b32 v152, v137, v150
	ds_bpermute_b32 v153, v137, v151
	s_waitcnt lgkmcnt(0)
	v_cndmask_b32_e64 v110, v148, v76, s[74:75]
	v_cndmask_b32_e64 v111, v149, v77, s[74:75]
	v_cndmask_b32_e64 v108, v108, v148, s[74:75]
	v_cndmask_b32_e64 v109, v109, v149, s[74:75]
	global_store_dwordx4 v139, v[108:111], s[68:69]
	v_cndmask_b32_e64 v42, v152, v12, s[74:75]
	v_cndmask_b32_e64 v43, v153, v13, s[74:75]
	v_cndmask_b32_e64 v40, v40, v152, s[74:75]
	v_cndmask_b32_e64 v41, v41, v153, s[74:75]
	global_store_dwordx4 v139, v[40:43], s[68:69] offset:256
	global_store_dwordx4 v133, v[104:107], s[8:9]
	global_store_dwordx4 v133, v[72:75], s[8:9] offset:64
	global_store_dwordx4 v133, v[32:35], s[8:9] offset:512
	global_store_dwordx4 v133, v[8:11], s[8:9] offset:576
	v_lshrrev_b32_e32 v139, 1, v133
	v_add_u32_e32 v139, v139, v144
	v_pk_mul_f32 v[104:105], v[104:105], v[214:215] op_sel_hi:[1,0]
	v_pk_mul_f32 v[106:107], v[106:107], v[214:215] op_sel_hi:[1,0]
	v_pk_mul_f32 v[104:105], v[180:181], v[104:105]
	v_pk_mul_f32 v[106:107], v[182:183], v[106:107]
	v_pk_fma_f32 v[104:105], v[220:221], v[104:105], v[240:241]
	v_pk_fma_f32 v[106:107], v[222:223], v[106:107], v[242:243]
	v_cvt_pk_bf16_f32 v104, v104, v105
	v_cvt_pk_bf16_f32 v105, v106, v107
	v_pk_mul_f32 v[72:73], v[72:73], v[214:215] op_sel_hi:[1,0]
	v_pk_mul_f32 v[74:75], v[74:75], v[214:215] op_sel_hi:[1,0]
	v_pk_mul_f32 v[72:73], v[184:185], v[72:73]
	v_pk_mul_f32 v[74:75], v[186:187], v[74:75]
	v_pk_fma_f32 v[72:73], v[224:225], v[72:73], v[244:245]
	v_pk_fma_f32 v[74:75], v[226:227], v[74:75], v[246:247]
	v_cvt_pk_bf16_f32 v72, v72, v73
	v_cvt_pk_bf16_f32 v73, v74, v75
	v_pk_mul_f32 v[32:33], v[32:33], v[214:215] op_sel_hi:[1,0]
	v_pk_mul_f32 v[34:35], v[34:35], v[214:215] op_sel_hi:[1,0]
	v_pk_mul_f32 v[32:33], v[188:189], v[32:33]
	v_pk_mul_f32 v[34:35], v[190:191], v[34:35]
	v_pk_fma_f32 v[32:33], v[232:233], v[32:33], v[156:157]
	v_pk_fma_f32 v[34:35], v[234:235], v[34:35], v[158:159]
	v_cvt_pk_bf16_f32 v32, v32, v33
	v_cvt_pk_bf16_f32 v33, v34, v35
	v_pk_mul_f32 v[8:9], v[8:9], v[214:215] op_sel_hi:[1,0]
	v_pk_mul_f32 v[10:11], v[10:11], v[214:215] op_sel_hi:[1,0]
	v_pk_mul_f32 v[8:9], v[192:193], v[8:9]
	v_pk_mul_f32 v[10:11], v[194:195], v[10:11]
	v_pk_fma_f32 v[8:9], v[236:237], v[8:9], v[160:161]
	v_pk_fma_f32 v[10:11], v[238:239], v[10:11], v[162:163]
	v_cvt_pk_bf16_f32 v8, v8, v9
	v_cvt_pk_bf16_f32 v9, v10, v11
	v_cndmask_b32_e64 v146, v72, v104, s[74:75]
	v_cndmask_b32_e64 v147, v73, v105, s[74:75]
	ds_bpermute_b32 v148, v137, v146
	ds_bpermute_b32 v149, v137, v147
	v_cndmask_b32_e64 v150, v8, v32, s[74:75]
	v_cndmask_b32_e64 v151, v9, v33, s[74:75]
	ds_bpermute_b32 v152, v137, v150
	ds_bpermute_b32 v153, v137, v151
	s_waitcnt lgkmcnt(0)
	v_cndmask_b32_e64 v106, v148, v72, s[74:75]
	v_cndmask_b32_e64 v107, v149, v73, s[74:75]
	v_cndmask_b32_e64 v104, v104, v148, s[74:75]
	v_cndmask_b32_e64 v105, v105, v149, s[74:75]
	global_store_dwordx4 v139, v[104:107], s[68:69]
	v_cndmask_b32_e64 v34, v152, v8, s[74:75]
	v_cndmask_b32_e64 v35, v153, v9, s[74:75]
	v_cndmask_b32_e64 v32, v32, v152, s[74:75]
	v_cndmask_b32_e64 v33, v33, v153, s[74:75]
	global_store_dwordx4 v139, v[32:35], s[68:69] offset:256
	global_store_dwordx4 v134, v[92:95], s[8:9]
	global_store_dwordx4 v134, v[60:63], s[8:9] offset:64
	global_store_dwordx4 v134, v[24:27], s[8:9] offset:512
	global_store_dwordx4 v134, v[4:7], s[8:9] offset:576
	v_lshrrev_b32_e32 v139, 1, v134
	v_add_u32_e32 v139, v139, v144
	v_pk_mul_f32 v[92:93], v[92:93], v[216:217] op_sel_hi:[1,0]
	v_pk_mul_f32 v[94:95], v[94:95], v[216:217] op_sel_hi:[1,0]
	v_pk_mul_f32 v[92:93], v[180:181], v[92:93]
	v_pk_mul_f32 v[94:95], v[182:183], v[94:95]
	v_pk_fma_f32 v[92:93], v[220:221], v[92:93], v[240:241]
	v_pk_fma_f32 v[94:95], v[222:223], v[94:95], v[242:243]
	v_cvt_pk_bf16_f32 v92, v92, v93
	v_cvt_pk_bf16_f32 v93, v94, v95
	v_pk_mul_f32 v[60:61], v[60:61], v[216:217] op_sel_hi:[1,0]
	v_pk_mul_f32 v[62:63], v[62:63], v[216:217] op_sel_hi:[1,0]
	v_pk_mul_f32 v[60:61], v[184:185], v[60:61]
	v_pk_mul_f32 v[62:63], v[186:187], v[62:63]
	v_pk_fma_f32 v[60:61], v[224:225], v[60:61], v[244:245]
	v_pk_fma_f32 v[62:63], v[226:227], v[62:63], v[246:247]
	v_cvt_pk_bf16_f32 v60, v60, v61
	v_cvt_pk_bf16_f32 v61, v62, v63
	v_pk_mul_f32 v[24:25], v[24:25], v[216:217] op_sel_hi:[1,0]
	v_pk_mul_f32 v[26:27], v[26:27], v[216:217] op_sel_hi:[1,0]
	v_pk_mul_f32 v[24:25], v[188:189], v[24:25]
	v_pk_mul_f32 v[26:27], v[190:191], v[26:27]
	v_pk_fma_f32 v[24:25], v[232:233], v[24:25], v[156:157]
	v_pk_fma_f32 v[26:27], v[234:235], v[26:27], v[158:159]
	v_cvt_pk_bf16_f32 v24, v24, v25
	v_cvt_pk_bf16_f32 v25, v26, v27
	v_pk_mul_f32 v[4:5], v[4:5], v[216:217] op_sel_hi:[1,0]
	v_pk_mul_f32 v[6:7], v[6:7], v[216:217] op_sel_hi:[1,0]
	v_pk_mul_f32 v[4:5], v[192:193], v[4:5]
	v_pk_mul_f32 v[6:7], v[194:195], v[6:7]
	v_pk_fma_f32 v[4:5], v[236:237], v[4:5], v[160:161]
	v_pk_fma_f32 v[6:7], v[238:239], v[6:7], v[162:163]
	v_cvt_pk_bf16_f32 v4, v4, v5
	v_cvt_pk_bf16_f32 v5, v6, v7
	v_cndmask_b32_e64 v146, v60, v92, s[74:75]
	v_cndmask_b32_e64 v147, v61, v93, s[74:75]
	ds_bpermute_b32 v148, v137, v146
	ds_bpermute_b32 v149, v137, v147
	v_cndmask_b32_e64 v150, v4, v24, s[74:75]
	v_cndmask_b32_e64 v151, v5, v25, s[74:75]
	ds_bpermute_b32 v152, v137, v150
	ds_bpermute_b32 v153, v137, v151
	s_waitcnt lgkmcnt(0)
	v_cndmask_b32_e64 v94, v148, v60, s[74:75]
	v_cndmask_b32_e64 v95, v149, v61, s[74:75]
	v_cndmask_b32_e64 v92, v92, v148, s[74:75]
	v_cndmask_b32_e64 v93, v93, v149, s[74:75]
	global_store_dwordx4 v139, v[92:95], s[68:69]
	v_cndmask_b32_e64 v26, v152, v4, s[74:75]
	v_cndmask_b32_e64 v27, v153, v5, s[74:75]
	v_cndmask_b32_e64 v24, v24, v152, s[74:75]
	v_cndmask_b32_e64 v25, v25, v153, s[74:75]
	global_store_dwordx4 v139, v[24:27], s[68:69] offset:256
	global_store_dwordx4 v135, v[84:87], s[8:9]
	global_store_dwordx4 v135, v[56:59], s[8:9] offset:64
	global_store_dwordx4 v135, v[16:19], s[8:9] offset:512
	global_store_dwordx4 v135, v[0:3], s[8:9] offset:576
	v_lshrrev_b32_e32 v139, 1, v135
	v_add_u32_e32 v139, v139, v144
	v_pk_mul_f32 v[84:85], v[84:85], v[218:219] op_sel_hi:[1,0]
	v_pk_mul_f32 v[86:87], v[86:87], v[218:219] op_sel_hi:[1,0]
	v_pk_mul_f32 v[84:85], v[180:181], v[84:85]
	v_pk_mul_f32 v[86:87], v[182:183], v[86:87]
	v_pk_fma_f32 v[84:85], v[220:221], v[84:85], v[240:241]
	v_pk_fma_f32 v[86:87], v[222:223], v[86:87], v[242:243]
	v_cvt_pk_bf16_f32 v84, v84, v85
	v_cvt_pk_bf16_f32 v85, v86, v87
	v_pk_mul_f32 v[56:57], v[56:57], v[218:219] op_sel_hi:[1,0]
	v_pk_mul_f32 v[58:59], v[58:59], v[218:219] op_sel_hi:[1,0]
	v_pk_mul_f32 v[56:57], v[184:185], v[56:57]
	v_pk_mul_f32 v[58:59], v[186:187], v[58:59]
	v_pk_fma_f32 v[56:57], v[224:225], v[56:57], v[244:245]
	v_pk_fma_f32 v[58:59], v[226:227], v[58:59], v[246:247]
	v_cvt_pk_bf16_f32 v56, v56, v57
	v_cvt_pk_bf16_f32 v57, v58, v59
	v_pk_mul_f32 v[16:17], v[16:17], v[218:219] op_sel_hi:[1,0]
	v_pk_mul_f32 v[18:19], v[18:19], v[218:219] op_sel_hi:[1,0]
	v_pk_mul_f32 v[16:17], v[188:189], v[16:17]
	v_pk_mul_f32 v[18:19], v[190:191], v[18:19]
	v_pk_fma_f32 v[16:17], v[232:233], v[16:17], v[156:157]
	v_pk_fma_f32 v[18:19], v[234:235], v[18:19], v[158:159]
	v_cvt_pk_bf16_f32 v16, v16, v17
	v_cvt_pk_bf16_f32 v17, v18, v19
	v_pk_mul_f32 v[0:1], v[0:1], v[218:219] op_sel_hi:[1,0]
	v_pk_mul_f32 v[2:3], v[2:3], v[218:219] op_sel_hi:[1,0]
	v_pk_mul_f32 v[0:1], v[192:193], v[0:1]
	v_pk_mul_f32 v[2:3], v[194:195], v[2:3]
	v_pk_fma_f32 v[0:1], v[236:237], v[0:1], v[160:161]
	v_pk_fma_f32 v[2:3], v[238:239], v[2:3], v[162:163]
	v_cvt_pk_bf16_f32 v0, v0, v1
	v_cvt_pk_bf16_f32 v1, v2, v3
	v_cndmask_b32_e64 v146, v56, v84, s[74:75]
	v_cndmask_b32_e64 v147, v57, v85, s[74:75]
	ds_bpermute_b32 v148, v137, v146
	ds_bpermute_b32 v149, v137, v147
	v_cndmask_b32_e64 v150, v0, v16, s[74:75]
	v_cndmask_b32_e64 v151, v1, v17, s[74:75]
	ds_bpermute_b32 v152, v137, v150
	ds_bpermute_b32 v153, v137, v151
	s_waitcnt lgkmcnt(0)
	v_cndmask_b32_e64 v86, v148, v56, s[74:75]
	v_cndmask_b32_e64 v87, v149, v57, s[74:75]
	v_cndmask_b32_e64 v84, v84, v148, s[74:75]
	v_cndmask_b32_e64 v85, v85, v149, s[74:75]
	global_store_dwordx4 v139, v[84:87], s[68:69]
	v_cndmask_b32_e64 v18, v152, v0, s[74:75]
	v_cndmask_b32_e64 v19, v153, v1, s[74:75]
	v_cndmask_b32_e64 v16, v16, v152, s[74:75]
	v_cndmask_b32_e64 v17, v17, v153, s[74:75]
	global_store_dwordx4 v139, v[16:19], s[68:69] offset:256
	s_mov_b64 s[38:39], -1
	s_andn2_b64 vcc, exec, s[6:7]
	s_cbranch_vccnz .LBB0_1192
	s_andn2_b64 vcc, exec, s[0:1]
	s_cbranch_vccnz .LBB0_1191
	s_barrier
	s_branch .LBB0_1191
